# v48 + packed f32 VALU ops in the FFN-up conv epilogue split into scalar v_mul/v_fma/v_add pairs (bit-identical)
# baseline (speedup 1.0000x reference)
; #define PG8_LAS __attribute__((address_space(3)))
; __device__ __forceinline__ float rstd2048(const stat_t* rs, int row) { return rsqrtf((float)rs[row] * (STAT_INV / 2048.0f) + NORM_EPS); }
;     __device__ __forceinline__ void operator()(const f32x4 (&acc)[2][2][4][2], const Unit& u, int wr, int wc, int fr_, int fq_) const {
;     ...
;         f32x4 swv[2][2];
; #pragma unroll
;         for (int bj = 0; bj < 2; ++bj)
; #pragma unroll
;             for (int n = 0; n < 2; ++n) swv[bj][n] = *(const f32x4*)(sw + u.pn * BM + bj * HALF + wc * 32 + 8 * fq + 4 * n);
; #pragma unroll
;         for (int ai = 0; ai < 2; ++ai)
; #pragma unroll
;             for (int m = 0; m < 4; ++m) { const float r = rstd2048(rs, rowb + ai * HALF + m) * sx[rowb + ai * HALF + m];
; #pragma unroll
;                 for (int bj = 0; bj < 2; ++bj)
; #pragma unroll
;                     for (int n = 0; n < 2; ++n) { typedef int i32x4 __attribute__((ext_vector_type(4)));
;                         z[ai][bj][m][n] = __builtin_convertvector(__builtin_bit_cast(i32x4, acc[ai][bj][m][n]), f32x4) * (swv[bj][n] * r); } }
;         PG8_LAS f32x4* X4 = (PG8_LAS f32x4*)xch;
;     ...
; #pragma unroll
;         for (int ai = 0; ai < 2; ++ai) {
;             if (fr == 0) {
; #pragma unroll
;                 for (int bj = 0; bj < 2; ++bj)
; #pragma unroll
;                     for (int n = 0; n < 2; ++n) X4[XIDX(wr, ai, 0) + bj * 2 + n] = z[ai][bj][0][n]; }
;             if (fr == 15) {
; #pragma unroll
;                 for (int bj = 0; bj < 2; ++bj)
; #pragma unroll
;                     for (int n = 0; n < 2; ++n) X4[XIDX(wr, ai, 1) + bj * 2 + n] = z[ai][bj][3][n]; }
.LBB0_83:
	s_lshl_b32 s66, s70, 8
	s_ashr_i32 s67, s66, 31
	v_mov_b32_e32 v174, v240
	v_mov_b32_e32 v175, v241
	s_lshl_b64 s[0:1], s[66:67], 2
	v_readlane_b32 s4, v255, 3
	s_add_u32 s0, s4, s0
	v_readlane_b32 s4, v255, 4
	v_lshlrev_b32_e32 v168, 3, v175
	s_addc_u32 s1, s4, s1
	v_ashrrev_i32_e32 v169, 31, v168
	v_lshl_add_u64 v[34:35], v[168:169], 2, s[0:1]
	s_lshl_b32 s0, s10, 8
	v_readlane_b32 s1, v254, 61
	s_add_i32 s0, s0, s1
	v_lshl_add_u32 v220, v174, 2, s0
	v_readlane_b32 s0, v254, 59
	v_ashrrev_i32_e32 v221, 31, v220
	v_readlane_b32 s1, v254, 60
	global_load_dwordx4 v[18:21], v[34:35], off offset:16
	global_load_dwordx4 v[38:41], v[34:35], off
	global_load_dwordx4 v[22:25], v[34:35], off offset:528
	s_nop 0
	global_load_dwordx4 v[34:37], v[34:35], off offset:512
	v_lshl_add_u64 v[172:173], v[220:221], 3, s[0:1]
	global_load_dwordx4 v[154:157], v[172:173], off offset:16
	global_load_dwordx4 v[164:167], v[172:173], off
	v_readlane_b32 s0, v252, 39
	v_readlane_b32 s1, v252, 40
	v_cvt_f32_i32_e32 v95, v95
	v_cvt_f32_i32_e32 v94, v94
	v_lshl_add_u64 v[170:171], v[220:221], 2, s[0:1]
	global_load_dwordx4 v[158:161], v[170:171], off
	v_cvt_f32_i32_e32 v97, v97
	v_cvt_f32_i32_e32 v96, v96
	v_cvt_f32_i32_e32 v59, v59
	v_cvt_f32_i32_e32 v58, v58
	v_cvt_f32_i32_e32 v61, v61
	v_cvt_f32_i32_e32 v60, v60
	v_cvt_f32_i32_e32 v79, v79
	v_cvt_f32_i32_e32 v78, v78
	v_cvt_f32_i32_e32 v81, v81
	v_cvt_f32_i32_e32 v80, v80
	v_cvt_f32_i32_e32 v63, v63
	v_cvt_f32_i32_e32 v62, v62
	v_cvt_f32_i32_e32 v65, v65
	v_cvt_f32_i32_e32 v64, v64
	v_lshlrev_b32_e32 v205, 6, v175
	v_cmp_lt_i32_e64 s[12:13], 14, v174
	s_mov_b64 s[6:7], 0
	s_waitcnt vmcnt(0)
	v_ffbh_u32_e32 v130, v165
	v_min_u32_e32 v132, 32, v130
	v_lshlrev_b64 v[130:131], v132, v[164:165]
	v_min_u32_e32 v130, 1, v130
	v_or_b32_e32 v130, v131, v130
	v_cvt_f32_u32_e32 v130, v130
	v_sub_u32_e32 v131, 32, v132
	v_ldexp_f32 v130, v130, v131
	v_fmamk_f32 v169, v130, 0x2e000000, v204
	v_ffbh_u32_e32 v130, v157
	v_min_u32_e32 v132, 32, v130
	v_lshlrev_b64 v[130:131], v132, v[156:157]
	v_min_u32_e32 v130, 1, v130
	v_or_b32_e32 v130, v131, v130
	v_cvt_f32_u32_e32 v130, v130
	v_sub_u32_e32 v131, 32, v132
	v_cmp_gt_f32_e32 vcc, s17, v169
	v_ldexp_f32 v130, v130, v131
	v_fmamk_f32 v130, v130, 0x2e000000, v204
	v_cmp_gt_f32_e64 s[0:1], s17, v130
	v_mul_f32_e32 v131, 0x4b800000, v130
	s_nop 0
	v_cndmask_b32_e64 v130, v130, v131, s[0:1]
	v_rsq_f32_e32 v130, v130
	s_nop 0
	v_mul_f32_e32 v131, 0x45800000, v130
	v_cndmask_b32_e64 v130, v130, v131, s[0:1]
	v_mul_f32_e32 v156, v161, v130
	v_mul_f32 v130, v38, v156
	v_mul_f32 v131, v39, v156
	v_mul_f32 v132, v40, v156
	v_mul_f32 v133, v41, v156
	v_mul_f32 v130, v130, v94
	v_mul_f32 v131, v131, v95
	v_mul_f32 v132, v132, v96
	v_mul_f32 v133, v133, v97
	v_mul_f32 v94, v18, v156
	v_mul_f32 v95, v19, v156
	v_mul_f32 v96, v20, v156
	v_mul_f32 v97, v21, v156
	v_mul_f32 v58, v94, v58
	v_mul_f32 v59, v95, v59
	v_mul_f32 v60, v96, v60
	v_mul_f32 v61, v97, v61
	v_mul_f32 v94, v34, v156
	v_mul_f32 v95, v35, v156
	v_mul_f32 v96, v36, v156
	v_mul_f32 v97, v37, v156
	v_mul_f32 v134, v94, v78
	v_mul_f32 v135, v95, v79
	v_mul_f32 v136, v96, v80
	v_mul_f32 v137, v97, v81
	v_mul_f32 v78, v22, v156
	v_mul_f32 v79, v23, v156
	v_mul_f32 v80, v24, v156
	v_mul_f32 v81, v25, v156
	v_mul_f32 v62, v78, v62
	v_mul_f32 v63, v79, v63
	v_mul_f32 v64, v80, v64
	v_mul_f32 v65, v81, v65
	global_load_dwordx4 v[162:165], v[172:173], off offset:1040
	global_load_dwordx4 v[78:81], v[172:173], off offset:1024
	s_waitcnt vmcnt(0)
	v_ffbh_u32_e32 v94, v79
	v_min_u32_e32 v94, 32, v94
	v_lshlrev_b64 v[78:79], v94, v[78:79]
	v_min_u32_e32 v78, 1, v78
	v_or_b32_e32 v78, v79, v78
	v_sub_u32_e32 v79, 32, v94
	global_load_dwordx4 v[94:97], v[170:171], off offset:512
	v_cvt_f32_u32_e32 v78, v78
	v_ldexp_f32 v78, v78, v79
	v_ffbh_u32_e32 v79, v165
	v_min_u32_e32 v79, 32, v79
	v_lshlrev_b64 v[156:157], v79, v[164:165]
	v_min_u32_e32 v156, 1, v156
	v_or_b32_e32 v156, v157, v156
	v_cvt_f32_u32_e32 v156, v156
	v_sub_u32_e32 v79, 32, v79
	v_fmamk_f32 v78, v78, 0x2e000000, v204
	v_cmp_gt_f32_e64 s[0:1], s17, v78
	v_ldexp_f32 v79, v156, v79
	v_fmamk_f32 v79, v79, 0x2e000000, v204
	v_cmp_gt_f32_e64 s[8:9], s17, v79
	s_and_saveexec_b64 s[82:83], s[12:13]
	s_xor_b64 s[96:97], exec, s[82:83]
	s_cbranch_execz .LBB0_87
	v_cmp_eq_u32_e64 s[12:13], 15, v174
	s_and_saveexec_b64 s[82:83], s[12:13]
	s_cbranch_execz .LBB0_86
	v_readlane_b32 s4, v255, 6
	s_mov_b64 s[6:7], exec
	s_nop 0
	v_add_u32_e32 v156, s4, v205
	ds_write_b128 v156, v[130:133] offset:256
	ds_write_b128 v156, v[58:61] offset:272
	ds_write_b128 v156, v[134:137] offset:288
	ds_write_b128 v156, v[62:65] offset:304

; #define PG8_LAS __attribute__((address_space(3)))
; __device__ __forceinline__ float rstd2048(const stat_t* rs, int row) { return rsqrtf((float)rs[row] * (STAT_INV / 2048.0f) + NORM_EPS); }
;     __device__ __forceinline__ void operator()(const f32x4 (&acc)[2][2][4][2], const Unit& u, int wr, int wc, int fr_, int fq_) const {
;     ...
;             for (int m = 0; m < 4; ++m) { const float r = rstd2048(rs, rowb + ai * HALF + m) * sx[rowb + ai * HALF + m];
; #pragma unroll
;                 for (int bj = 0; bj < 2; ++bj)
; #pragma unroll
;                     for (int n = 0; n < 2; ++n) { typedef int i32x4 __attribute__((ext_vector_type(4)));
;                         z[ai][bj][m][n] = __builtin_convertvector(__builtin_bit_cast(i32x4, acc[ai][bj][m][n]), f32x4) * (swv[bj][n] * r); } }
;         PG8_LAS f32x4* X4 = (PG8_LAS f32x4*)xch;
;     ...
; #pragma unroll
;         for (int ai = 0; ai < 2; ++ai) {
;             if (fr == 0) {
; #pragma unroll
;                 for (int bj = 0; bj < 2; ++bj)
; #pragma unroll
;                     for (int n = 0; n < 2; ++n) X4[XIDX(wr, ai, 0) + bj * 2 + n] = z[ai][bj][0][n]; }
.LBB0_87:
	s_or_saveexec_b64 s[12:13], s[96:97]
	v_mul_f32_e32 v156, 0x4b800000, v169
	v_cndmask_b32_e32 v156, v169, v156, vcc
	v_rsq_f32_e32 v156, v156
	v_cvt_f32_i32_e32 v151, v151
	v_cvt_f32_i32_e32 v150, v150
	v_cvt_f32_i32_e32 v153, v153
	v_mul_f32_e32 v157, 0x45800000, v156
	v_cvt_f32_i32_e32 v152, v152
	v_cndmask_b32_e32 v156, v156, v157, vcc
	v_cvt_f32_i32_e32 v147, v147
	v_cvt_f32_i32_e32 v146, v146
	v_mul_f32_e32 v156, v158, v156
	v_cvt_f32_i32_e32 v149, v149
	v_cvt_f32_i32_e32 v148, v148
	v_cvt_f32_i32_e32 v143, v143
	v_cvt_f32_i32_e32 v142, v142
	v_mul_f32 v164, v38, v156
	v_mul_f32 v165, v39, v156
	v_cvt_f32_i32_e32 v145, v145
	v_cvt_f32_i32_e32 v144, v144
	v_cvt_f32_i32_e32 v139, v139
	v_cvt_f32_i32_e32 v141, v141
	v_cvt_f32_i32_e32 v140, v140
	v_cvt_f32_i32_e32 v138, v138
	v_mul_f32 v170, v40, v156
	v_mul_f32 v171, v41, v156
	v_mul_f32 v150, v164, v150
	v_mul_f32 v151, v165, v151
	v_mul_f32 v164, v18, v156
	v_mul_f32 v165, v19, v156
	v_mul_f32 v152, v170, v152
	v_mul_f32 v153, v171, v153
	v_mul_f32 v170, v20, v156
	v_mul_f32 v171, v21, v156
	v_mul_f32 v146, v164, v146
	v_mul_f32 v147, v165, v147
	v_mul_f32 v164, v34, v156
	v_mul_f32 v165, v35, v156
	v_mul_f32 v148, v170, v148
	v_mul_f32 v149, v171, v149
	v_mul_f32 v170, v36, v156
	v_mul_f32 v171, v37, v156
	v_mul_f32 v142, v164, v142
	v_mul_f32 v143, v165, v143
	v_mul_f32 v164, v22, v156
	v_mul_f32 v165, v23, v156
	v_mul_f32 v157, v25, v156
	v_mul_f32 v156, v24, v156
	v_mul_f32 v144, v170, v144
	v_mul_f32 v145, v171, v145
	v_mul_f32 v140, v156, v140
	v_mul_f32 v141, v157, v141
	v_mul_f32 v138, v164, v138
	v_mul_f32 v139, v165, v139
	v_add_u32_e32 v156, s39, v205
	s_xor_b64 exec, exec, s[12:13]
	s_cbranch_execz .LBB0_91
	v_cmp_eq_u32_e32 vcc, 0, v174
	s_mov_b64 s[96:97], s[6:7]
	s_and_saveexec_b64 s[82:83], vcc
	s_cbranch_execz .LBB0_90
	v_readlane_b32 s4, v255, 5
	s_or_b64 s[96:97], s[6:7], exec
	s_nop 0
	v_add_u32_e32 v157, s4, v156
	ds_write_b128 v157, v[150:153]
	ds_write_b128 v157, v[146:149] offset:16
	ds_write_b128 v157, v[142:145] offset:32
	ds_write_b128 v157, v[138:141] offset:48

; #define PG8_LAS __attribute__((address_space(3)))
; __device__ __forceinline__ float rstd2048(const stat_t* rs, int row) { return rsqrtf((float)rs[row] * (STAT_INV / 2048.0f) + NORM_EPS); }
;     __device__ __forceinline__ void operator()(const f32x4 (&acc)[2][2][4][2], const Unit& u, int wr, int wc, int fr_, int fq_) const {
;     ...
;             for (int m = 0; m < 4; ++m) { const float r = rstd2048(rs, rowb + ai * HALF + m) * sx[rowb + ai * HALF + m];
; #pragma unroll
;                 for (int bj = 0; bj < 2; ++bj)
; #pragma unroll
;                     for (int n = 0; n < 2; ++n) { typedef int i32x4 __attribute__((ext_vector_type(4)));
;                         z[ai][bj][m][n] = __builtin_convertvector(__builtin_bit_cast(i32x4, acc[ai][bj][m][n]), f32x4) * (swv[bj][n] * r); } }
;         PG8_LAS f32x4* X4 = (PG8_LAS f32x4*)xch;
;     ...
; #pragma unroll
;         for (int ai = 0; ai < 2; ++ai) {
;             if (fr == 0) {
; #pragma unroll
;                 for (int bj = 0; bj < 2; ++bj)
; #pragma unroll
;                     for (int n = 0; n < 2; ++n) X4[XIDX(wr, ai, 0) + bj * 2 + n] = z[ai][bj][0][n]; }
;             if (fr == 15) {
; #pragma unroll
;                 for (int bj = 0; bj < 2; ++bj)
; #pragma unroll
;                     for (int n = 0; n < 2; ++n) X4[XIDX(wr, ai, 1) + bj * 2 + n] = z[ai][bj][3][n]; }
.LBB0_91:
	s_or_b64 exec, exec, s[12:13]
	v_mul_f32_e32 v157, 0x4b800000, v78
	v_cndmask_b32_e64 v78, v78, v157, s[0:1]
	v_rsq_f32_e32 v78, v78
	v_cvt_f32_i32_e32 v107, v107
	v_cvt_f32_i32_e32 v106, v106
	v_cvt_f32_i32_e32 v109, v109
	v_mul_f32_e32 v157, 0x45800000, v78
	v_cvt_f32_i32_e32 v108, v108
	v_cndmask_b32_e64 v78, v78, v157, s[0:1]
	v_cvt_f32_i32_e32 v47, v47
	v_cvt_f32_i32_e32 v46, v46
	s_waitcnt vmcnt(0)
	v_mul_f32_e32 v78, v94, v78
	v_cvt_f32_i32_e32 v49, v49
	v_cvt_f32_i32_e32 v48, v48
	v_cvt_f32_i32_e32 v115, v115
	v_cvt_f32_i32_e32 v114, v114
	v_mul_f32 v164, v38, v78
	v_mul_f32 v165, v39, v78
	v_mul_f32 v170, v40, v78
	v_mul_f32 v171, v41, v78
	v_mul_f32 v106, v164, v106
	v_mul_f32 v107, v165, v107
	v_mul_f32 v164, v18, v78
	v_mul_f32 v165, v19, v78
	v_mul_f32 v108, v170, v108
	v_mul_f32 v109, v171, v109
	v_mul_f32 v170, v20, v78
	v_mul_f32 v171, v21, v78
	v_mul_f32 v46, v164, v46
	v_mul_f32 v47, v165, v47
	v_mul_f32 v164, v34, v78
	v_mul_f32 v165, v35, v78
	v_mul_f32_e32 v94, 0x4b800000, v79
	v_mul_f32 v48, v170, v48
	v_mul_f32 v49, v171, v49
	v_mul_f32 v170, v36, v78
	v_mul_f32 v171, v37, v78
	v_mul_f32 v114, v164, v114
	v_mul_f32 v115, v165, v115
	v_mul_f32 v164, v22, v78
	v_mul_f32 v165, v23, v78
	v_cndmask_b32_e64 v79, v79, v94, s[8:9]
	v_cvt_f32_i32_e32 v53, v53
	v_cvt_f32_i32_e32 v52, v52
	v_rsq_f32_e32 v94, v79
	v_cvt_f32_i32_e32 v51, v51
	v_cvt_f32_i32_e32 v50, v50
	v_mul_f32 v79, v25, v78
	v_mul_f32 v78, v24, v78
	v_cvt_f32_i32_e32 v117, v117
	v_cvt_f32_i32_e32 v116, v116
	v_mul_f32 v52, v78, v52
	v_mul_f32 v53, v79, v53
	v_mul_f32_e32 v78, 0x45800000, v94
	v_cvt_f32_i32_e32 v127, v127
	v_cvt_f32_i32_e32 v126, v126
	v_cndmask_b32_e64 v78, v94, v78, s[8:9]
	v_cvt_f32_i32_e32 v129, v129
	v_cvt_f32_i32_e32 v128, v128
	v_cvt_f32_i32_e32 v67, v67
	v_cvt_f32_i32_e32 v66, v66
	v_mul_f32_e32 v78, v97, v78
	v_cvt_f32_i32_e32 v69, v69
	v_cvt_f32_i32_e32 v68, v68
	v_cvt_f32_i32_e32 v123, v123
	v_cvt_f32_i32_e32 v122, v122
	v_mul_f32 v50, v164, v50
	v_mul_f32 v51, v165, v51
	v_mul_f32 v164, v38, v78
	v_mul_f32 v165, v39, v78
	v_cvt_f32_i32_e32 v125, v125
	v_cvt_f32_i32_e32 v124, v124
	v_cvt_f32_i32_e32 v71, v71
	v_cvt_f32_i32_e32 v73, v73
	v_cvt_f32_i32_e32 v72, v72
	v_cvt_f32_i32_e32 v70, v70
	v_mul_f32 v116, v170, v116
	v_mul_f32 v117, v171, v117
	v_mul_f32 v170, v40, v78
	v_mul_f32 v171, v41, v78
	v_mul_f32 v126, v164, v126
	v_mul_f32 v127, v165, v127
	v_mul_f32 v164, v18, v78
	v_mul_f32 v165, v19, v78
	v_mul_f32 v128, v170, v128
	v_mul_f32 v129, v171, v129
	v_mul_f32 v170, v20, v78
	v_mul_f32 v171, v21, v78
	v_mul_f32 v66, v164, v66
	v_mul_f32 v67, v165, v67
	v_mul_f32 v164, v34, v78
	v_mul_f32 v165, v35, v78
	v_mul_f32 v68, v170, v68
	v_mul_f32 v69, v171, v69
	v_mul_f32 v170, v36, v78
	v_mul_f32 v171, v37, v78
	v_mul_f32 v122, v164, v122
	v_mul_f32 v123, v165, v123
	v_mul_f32 v164, v22, v78
	v_mul_f32 v165, v23, v78
	v_mul_f32 v79, v25, v78
	v_mul_f32 v78, v24, v78
	v_mul_f32 v124, v170, v124
	v_mul_f32 v125, v171, v125
	v_mul_f32 v72, v78, v72
	v_mul_f32 v73, v79, v73
	v_mul_f32 v70, v164, v70
	v_mul_f32 v71, v165, v71
	s_and_saveexec_b64 s[0:1], s[6:7]
	s_cbranch_execz .LBB0_97
	v_cmp_lt_i32_e32 vcc, 14, v174
	s_and_saveexec_b64 s[6:7], vcc
	s_xor_b64 s[6:7], exec, s[6:7]
	s_cbranch_execz .LBB0_94
	v_readlane_b32 s4, v255, 6
	s_nop 1
	v_add_u32_e32 v78, s4, v205
	ds_write_b128 v78, v[126:129] offset:768
	ds_write_b128 v78, v[66:69] offset:784
	ds_write_b128 v78, v[122:125] offset:800
	ds_write_b128 v78, v[70:73] offset:816

; #define PG8_LAS __attribute__((address_space(3)))
; __device__ __forceinline__ float rstd2048(const stat_t* rs, int row) { return rsqrtf((float)rs[row] * (STAT_INV / 2048.0f) + NORM_EPS); }
;     __device__ __forceinline__ void operator()(const f32x4 (&acc)[2][2][4][2], const Unit& u, int wr, int wc, int fr_, int fq_) const {
;     ...
;             for (int m = 0; m < 4; ++m) { const float r = rstd2048(rs, rowb + ai * HALF + m) * sx[rowb + ai * HALF + m];
; #pragma unroll
;                 for (int bj = 0; bj < 2; ++bj)
; #pragma unroll
;                     for (int n = 0; n < 2; ++n) { typedef int i32x4 __attribute__((ext_vector_type(4)));
;                         z[ai][bj][m][n] = __builtin_convertvector(__builtin_bit_cast(i32x4, acc[ai][bj][m][n]), f32x4) * (swv[bj][n] * r); } }
;         PG8_LAS f32x4* X4 = (PG8_LAS f32x4*)xch;
;     ...
; #pragma unroll
;         for (int ai = 0; ai < 2; ++ai) {
;             if (fr == 0) {
; #pragma unroll
;                 for (int bj = 0; bj < 2; ++bj)
; #pragma unroll
;                     for (int n = 0; n < 2; ++n) X4[XIDX(wr, ai, 0) + bj * 2 + n] = z[ai][bj][0][n]; }
;             if (fr == 15) {
; #pragma unroll
;                 for (int bj = 0; bj < 2; ++bj)
; #pragma unroll
;                     for (int n = 0; n < 2; ++n) X4[XIDX(wr, ai, 1) + bj * 2 + n] = z[ai][bj][3][n]; }
;         }
;         {   const int hcol = u.pn * BM + wc * 32 + 8 * fq;
;             if (wr == 0 && fr == 0) {
; #pragma unroll
;                 for (int m = 0; m < 2; ++m)
; #pragma unroll
;                     for (int bj = 0; bj < 2; ++bj)
; #pragma unroll
;                         for (int n = 0; n < 2; ++n) *(f32x4*)(HZ + (size_t)(u.pm * 4 + m) * NZ_ + hcol + bj * HALF + 4 * n) = z[0][bj][m][n]; }
;             if (wr == 1 && fr == 15) {
; #pragma unroll
;                 for (int m = 2; m < 4; ++m)
; #pragma unroll
;                     for (int bj = 0; bj < 2; ++bj)
; #pragma unroll
;                         for (int n = 0; n < 2; ++n) *(f32x4*)(HZ + (size_t)(u.pm * 4 + m) * NZ_ + hcol + bj * HALF + 4 * n) = z[1][bj][m][n]; }
.LBB0_97:
	s_or_b64 exec, exec, s[0:1]
	v_ffbh_u32_e32 v78, v167
	v_min_u32_e32 v94, 32, v78
	v_lshlrev_b64 v[78:79], v94, v[166:167]
	v_min_u32_e32 v78, 1, v78
	v_or_b32_e32 v78, v79, v78
	v_cvt_f32_u32_e32 v78, v78
	v_sub_u32_e32 v94, 32, v94
	v_cvt_f32_i32_e32 v79, v119
	v_cvt_f32_i32_e32 v119, v121
	v_ldexp_f32 v78, v78, v94
	v_fmamk_f32 v78, v78, 0x2e000000, v204
	v_mul_f32_e32 v94, 0x4b800000, v78
	v_cmp_gt_f32_e32 vcc, s17, v78
	v_cvt_f32_i32_e32 v113, v113
	v_cvt_f32_i32_e32 v112, v112
	v_cndmask_b32_e32 v78, v78, v94, vcc
	v_rsq_f32_e32 v94, v78
	v_cvt_f32_i32_e32 v78, v118
	v_cvt_f32_i32_e32 v118, v120
	v_cvt_f32_i32_e32 v105, v105
	v_mul_f32_e32 v97, 0x45800000, v94
	v_cndmask_b32_e32 v94, v94, v97, vcc
	v_mul_f32_e32 v94, v159, v94
	v_mul_f32 v156, v38, v94
	v_mul_f32 v157, v39, v94
	v_mul_f32 v120, v40, v94
	v_mul_f32 v121, v41, v94
	v_cvt_f32_i32_e32 v104, v104
	v_mul_f32 v120, v120, v118
	v_mul_f32 v121, v121, v119
	v_mul_f32 v118, v156, v78
	v_mul_f32 v119, v157, v79
	v_cvt_f32_i32_e32 v79, v111
	v_cvt_f32_i32_e32 v78, v110
	v_mul_f32 v110, v18, v94
	v_mul_f32 v111, v19, v94
	v_mul_f32 v156, v20, v94
	v_mul_f32 v157, v21, v94
	v_cvt_f32_i32_e32 v101, v101
	v_mul_f32 v110, v110, v78
	v_mul_f32 v111, v111, v79
	v_cvt_f32_i32_e32 v79, v103
	v_cvt_f32_i32_e32 v78, v102
	v_mul_f32 v112, v156, v112
	v_mul_f32 v113, v157, v113
	v_mul_f32 v102, v34, v94
	v_mul_f32 v103, v35, v94
	v_mul_f32 v156, v36, v94
	v_mul_f32 v157, v37, v94
	v_cvt_f32_i32_e32 v100, v100
	v_mul_f32 v158, v156, v104
	v_mul_f32 v159, v157, v105
	v_mul_f32 v156, v102, v78
	v_mul_f32 v157, v103, v79
	v_cvt_f32_i32_e32 v79, v99
	v_cvt_f32_i32_e32 v78, v98
	v_mul_f32 v98, v22, v94
	v_mul_f32 v99, v23, v94
	s_or_b32 s0, s66, s36
	v_mul_f32 v102, v24, v94
	v_mul_f32 v103, v25, v94
	v_mul_f32 v98, v98, v78
	v_mul_f32 v99, v99, v79
	v_add_u32_e32 v78, s0, v168
	v_readlane_b32 s0, v254, 58
	v_mul_f32 v100, v102, v100
	v_mul_f32 v101, v103, v101
	s_nop 0
	v_or_b32_e32 v79, s0, v174
	v_cmp_eq_u32_e32 vcc, 0, v79
	v_ashrrev_i32_e32 v79, 31, v78
	s_and_saveexec_b64 s[0:1], vcc
	s_cbranch_execz .LBB0_99
	s_lshl_b32 s4, s10, 2
	s_mul_i32 s5, s10, 0x2c000
	v_readlane_b32 s8, v252, 43
	s_mul_hi_i32 s7, s4, 0xb000
	v_readlane_b32 s9, v252, 44
	s_add_u32 s6, s8, s5
	s_addc_u32 s7, s9, s7
	s_or_b32 s4, s4, 1
	v_lshlrev_b64 v[102:103], 2, v[78:79]
	s_mul_hi_i32 s5, s4, 0xb000
	s_mul_i32 s4, s4, 0xb000
	v_lshl_add_u64 v[104:105], s[6:7], 0, v[102:103]
	s_add_u32 s6, s8, s4
	s_addc_u32 s7, s9, s5
	v_lshl_add_u64 v[102:103], s[6:7], 0, v[102:103]
	global_store_dwordx4 v[104:105], v[150:153], off
	global_store_dwordx4 v[104:105], v[146:149], off offset:16
	global_store_dwordx4 v[104:105], v[142:145], off offset:512
	global_store_dwordx4 v[104:105], v[138:141], off offset:528
	global_store_dwordx4 v[102:103], v[118:121], off
	global_store_dwordx4 v[102:103], v[110:113], off offset:16
	global_store_dwordx4 v[102:103], v[156:159], off offset:512
	global_store_dwordx4 v[102:103], v[98:101], off offset:528
.LBB0_99:
	s_or_b64 exec, exec, s[0:1]
	v_ffbh_u32_e32 v94, v163
	v_min_u32_e32 v94, 32, v94
	v_lshlrev_b64 v[102:103], v94, v[162:163]
	v_min_u32_e32 v97, 1, v102
	v_or_b32_e32 v97, v103, v97
	v_cvt_f32_u32_e32 v97, v97
	v_sub_u32_e32 v94, 32, v94
	v_cvt_f32_i32_e32 v91, v91
	v_cvt_f32_i32_e32 v90, v90
	v_ldexp_f32 v94, v97, v94
	v_fmamk_f32 v94, v94, 0x2e000000, v204
	v_mul_f32_e32 v97, 0x4b800000, v94
	v_cmp_gt_f32_e32 vcc, s17, v94
	v_cvt_f32_i32_e32 v93, v93
	v_cvt_f32_i32_e32 v92, v92
	v_cndmask_b32_e32 v94, v94, v97, vcc
	v_rsq_f32_e32 v94, v94
	v_cvt_f32_i32_e32 v87, v87
	v_cvt_f32_i32_e32 v89, v89
	v_cvt_f32_i32_e32 v88, v88
	v_mul_f32_e32 v97, 0x45800000, v94
	v_cndmask_b32_e32 v94, v94, v97, vcc
	v_cvt_f32_i32_e32 v86, v86
	v_mul_f32_e32 v94, v96, v94
	v_cvt_f32_i32_e32 v83, v83
	v_cvt_f32_i32_e32 v85, v85
	v_cvt_f32_i32_e32 v84, v84
	v_cvt_f32_i32_e32 v82, v82
	v_mul_f32 v96, v38, v94
	v_mul_f32 v97, v39, v94
	v_mul_f32 v102, v40, v94
	v_mul_f32 v103, v41, v94
	v_cvt_f32_i32_e32 v75, v75
	v_cvt_f32_i32_e32 v77, v77
	v_cvt_f32_i32_e32 v76, v76
	v_cvt_f32_i32_e32 v74, v74
	v_mul_f32 v92, v102, v92
	v_mul_f32 v93, v103, v93
	v_mul_f32 v90, v96, v90
	v_mul_f32 v91, v97, v91
	v_mul_f32 v96, v18, v94
	v_mul_f32 v97, v19, v94
	v_mul_f32 v102, v20, v94
	v_mul_f32 v103, v21, v94
	v_mul_f32 v86, v96, v86
	v_mul_f32 v87, v97, v87
	v_mul_f32 v88, v102, v88
	v_mul_f32 v89, v103, v89
	v_mul_f32 v96, v34, v94
	v_mul_f32 v97, v35, v94
	v_mul_f32 v102, v36, v94
	v_mul_f32 v103, v37, v94
	v_mul_f32 v82, v96, v82
	v_mul_f32 v83, v97, v83
	v_mul_f32 v84, v102, v84
	v_mul_f32 v85, v103, v85
	v_mul_f32 v96, v22, v94
	v_mul_f32 v97, v23, v94
	v_mul_f32 v102, v24, v94
	v_mul_f32 v103, v25, v94
	v_cmp_eq_u32_e32 vcc, 15, v174
	v_mul_f32 v76, v102, v76
	v_mul_f32 v77, v103, v77
	v_mul_f32 v74, v96, v74
	v_mul_f32 v75, v97, v75
	s_and_b64 s[6:7], s[46:47], vcc
	s_and_saveexec_b64 s[0:1], s[6:7]
	s_mov_b32 s12, s38
	s_cbranch_execz .LBB0_101
	s_lshl_b32 s4, s10, 2
	s_or_b32 s5, s4, 2
	s_mul_hi_i32 s7, s5, 0xb000
	s_mul_i32 s5, s5, 0xb000
	v_readlane_b32 s8, v252, 43
	v_readlane_b32 s9, v252, 44
	s_add_u32 s6, s8, s5
	s_addc_u32 s7, s9, s7
	s_or_b32 s4, s4, 3
	v_lshlrev_b64 v[78:79], 2, v[78:79]
	s_mul_hi_i32 s5, s4, 0xb000
	s_mul_i32 s4, s4, 0xb000
	v_lshl_add_u64 v[96:97], s[6:7], 0, v[78:79]
	s_add_u32 s6, s8, s4
	s_addc_u32 s7, s9, s5
	v_lshl_add_u64 v[78:79], s[6:7], 0, v[78:79]
	global_store_dwordx4 v[96:97], v[90:93], off
	global_store_dwordx4 v[96:97], v[86:89], off offset:16
	global_store_dwordx4 v[96:97], v[82:85], off offset:512
	global_store_dwordx4 v[96:97], v[74:77], off offset:528
	global_store_dwordx4 v[78:79], v[126:129], off
	global_store_dwordx4 v[78:79], v[66:69], off offset:16
	global_store_dwordx4 v[78:79], v[122:125], off offset:512
	global_store_dwordx4 v[78:79], v[70:73], off offset:528

;     __device__ __forceinline__ void operator()(const f32x4 (&acc)[2][2][4][2], const Unit& u, int wr, int wc, int fr_, int fq_) const {
;     ...
;             for (int n = 0; n < 2; ++n) {
;                 const int ch = ch0 + 4 * n;
;                 const f32x4 w0g = *(const f32x4*)(cw + ch), w1g = *(const f32x4*)(cw + NZ_ + ch), w2g = *(const f32x4*)(cw + 2 * NZ_ + ch), bg = *(const f32x4*)(cb + ch);
;                 const f32x4 w0u = *(const f32x4*)(cw + DFF_ + ch), w1u = *(const f32x4*)(cw + NZ_ + DFF_ + ch), w2u = *(const f32x4*)(cw + 2 * NZ_ + DFF_ + ch), bu = *(const f32x4*)(cb + DFF_ + ch);
;                 f32x4 pBg = zero4, pBu = zero4, nBg = zero4, nBu = zero4;
;                 if (wr == 1) { pBg = X4[XIDX(0, ai, 1) + n]; pBu = X4[XIDX(0, ai, 1) + 2 + n]; }
;                 else if (ai == 1) { pBg = X4[XIDX(1, 0, 1) + n]; pBu = X4[XIDX(1, 0, 1) + 2 + n]; }
;                 if (wr == 0) { nBg = X4[XIDX(1, ai, 0) + n]; nBu = X4[XIDX(1, ai, 0) + 2 + n]; }
;                 else if (ai == 0) { nBg = X4[XIDX(0, 1, 0) + n]; nBu = X4[XIDX(0, 1, 0) + 2 + n]; }
;                 float o[4][4];
; #pragma unroll
;                 for (int h = 0; h < 2; ++h) {
;                     typedef float f32x2 __attribute__((ext_vector_type(2)));
;     ...
;                     const f32x2 g0 = PAIR(z[ai][0][0][n]), g1 = PAIR(z[ai][0][1][n]), g2 = PAIR(z[ai][0][2][n]), g3 = PAIR(z[ai][0][3][n]);
;                     const f32x2 u0 = PAIR(z[ai][1][0][n]), u1 = PAIR(z[ai][1][1][n]), u2 = PAIR(z[ai][1][2][n]), u3 = PAIR(z[ai][1][3][n]);
;                     const f32x2 pBg2 = PAIR(pBg), nBg2 = PAIR(nBg), pBu2 = PAIR(pBu), nBu2 = PAIR(nBu);
;                     f32x2 pg, ng, pu, nu;
;                     pg.x = dpp_shr1(pBg2.x, g3.x); pg.y = dpp_shr1(pBg2.y, g3.y); ng.x = dpp_shl1(nBg2.x, g0.x); ng.y = dpp_shl1(nBg2.y, g0.y);
;                     pu.x = dpp_shr1(pBu2.x, u3.x); pu.y = dpp_shr1(pBu2.y, u3.y); nu.x = dpp_shl1(nBu2.x, u0.x); nu.y = dpp_shl1(nBu2.y, u0.y);
;                     const f32x2 A0 = PAIR(w0g), A1 = PAIR(w1g), A2 = PAIR(w2g), AB = PAIR(bg), C0 = PAIR(w0u), C1 = PAIR(w1u), C2 = PAIR(w2u), CB = PAIR(bu);
;                     f32x2 G[4], U[4];
;                     G[0] = A0 * pg + (A1 * g0 + (A2 * g1 + AB)); G[1] = A0 * g0 + (A1 * g1 + (A2 * g2 + AB)); G[2] = A0 * g1 + (A1 * g2 + (A2 * g3 + AB)); G[3] = A0 * g2 + (A1 * g3 + (A2 * ng + AB));
.LBB0_103:
	v_ffbh_u32_e32 v96, v155
	v_min_u32_e32 v103, 32, v96
	v_lshlrev_b64 v[96:97], v103, v[154:155]
	v_min_u32_e32 v96, 1, v96
	v_or_b32_e32 v96, v97, v96
	v_cvt_f32_u32_e32 v96, v96
	v_sub_u32_e32 v97, 32, v103
	v_cvt_f32_i32_e32 v43, v43
	v_cvt_f32_i32_e32 v42, v42
	v_ldexp_f32 v96, v96, v97
	v_fmamk_f32 v96, v96, 0x2e000000, v204
	v_cmp_gt_f32_e32 vcc, s17, v96
	v_mul_f32_e32 v97, 0x4b800000, v96
	v_cvt_f32_i32_e32 v45, v45
	v_cndmask_b32_e32 v96, v96, v97, vcc
	v_rsq_f32_e32 v96, v96
	v_cvt_f32_i32_e32 v44, v44
	v_readlane_b32 s0, v254, 63
	s_waitcnt vmcnt(4)
	v_fma_f32 v154, v118, v182, v190
	v_fma_f32 v155, v119, v183, v191
	v_mul_f32_e32 v97, 0x45800000, v96
	v_cndmask_b32_e32 v96, v96, v97, vcc
	v_mul_f32_e32 v238, v160, v96
	v_cvt_f32_i32_e32 v97, v55
	v_cvt_f32_i32_e32 v96, v54
	v_cvt_f32_i32_e32 v55, v57
	v_cvt_f32_i32_e32 v54, v56
	v_mul_f32 v104, v40, v238
	v_mul_f32 v105, v41, v238
	v_mul_f32 v56, v38, v238
	v_mul_f32 v57, v39, v238
	v_fma_f32 v154, v150, v174, v154
	v_fma_f32 v155, v151, v175, v155
	v_mul_f32 v54, v104, v54
	v_mul_f32 v55, v105, v55
	v_mul_f32 v104, v34, v238
	v_mul_f32 v105, v35, v238
	v_mul_f32 v96, v56, v96
	v_mul_f32 v97, v57, v97
	v_mul_f32 v56, v36, v238
	v_mul_f32 v57, v37, v238
	v_mul_f32 v104, v104, v42
	v_mul_f32 v105, v105, v43
	v_add_u32_e32 v42, s0, v94
	v_mul_f32 v56, v56, v44
	v_mul_f32 v57, v57, v45
	ds_read_b128 v[42:45], v42
	v_readlane_b32 s0, v254, 62
	v_fma_f32 v160, v96, v182, v190
	v_fma_f32 v161, v97, v183, v191
	s_waitcnt lgkmcnt(2)
	v_mov_b32_dpp v198, v130 row_shr:1 row_mask:0xf bank_mask:0xf
	v_add_u32_e32 v103, s0, v94
	ds_read_b128 v[244:247], v103
	s_waitcnt lgkmcnt(1)
	v_mov_b32_dpp v42, v150 row_shl:1 row_mask:0xf bank_mask:0xf
	v_mov_b32_dpp v43, v151 row_shl:1 row_mask:0xf bank_mask:0xf
	v_fma_f32 v160, v118, v174, v160
	v_fma_f32 v161, v119, v175, v161
	v_fma_f32 v42, v182, v42, v190
	v_fma_f32 v43, v183, v43, v191
	v_fma_f32 v150, v150, v166, v160
	v_fma_f32 v151, v151, v167, v161
	v_fma_f32 v160, v130, v182, v190
	v_fma_f32 v161, v131, v183, v191
	v_fma_f32 v42, v130, v174, v42
	v_fma_f32 v43, v131, v175, v43
	v_mov_b32_dpp v199, v131 row_shr:1 row_mask:0xf bank_mask:0xf
	v_fma_f32 v160, v96, v174, v160
	v_fma_f32 v161, v97, v175, v161
	v_fma_f32 v130, v96, v166, v42
	v_fma_f32 v131, v97, v167, v43
	s_waitcnt vmcnt(0)
	v_fma_f32 v96, v104, v178, v186
	v_fma_f32 v97, v105, v179, v187
	v_fma_f32 v42, v156, v178, v186
	v_fma_f32 v43, v157, v179, v187
	v_fma_f32 v96, v156, v170, v96
	v_fma_f32 v97, v157, v171, v97
	s_waitcnt lgkmcnt(0)
	v_mov_b32_dpp v244, v142 row_shl:1 row_mask:0xf bank_mask:0xf
	v_mov_b32_dpp v245, v143 row_shl:1 row_mask:0xf bank_mask:0xf
	v_fma_f32 v42, v142, v170, v42
	v_fma_f32 v43, v143, v171, v43
	v_fma_f32 v96, v142, v162, v96
	v_fma_f32 v97, v143, v163, v97
	v_fma_f32 v142, v134, v178, v186
	v_fma_f32 v143, v135, v179, v187
	v_mov_b32_dpp v194, v134 row_shr:1 row_mask:0xf bank_mask:0xf
	v_fma_f32 v142, v104, v170, v142
	v_fma_f32 v143, v105, v171, v143
	v_mov_b32_dpp v195, v135 row_shr:1 row_mask:0xf bank_mask:0xf
	v_fma_f32 v142, v156, v162, v142
	v_fma_f32 v143, v157, v163, v143
	v_fma_f32 v156, v178, v244, v186
	v_fma_f32 v157, v179, v245, v187
	v_fma_f32 v154, v166, v198, v154
	v_fma_f32 v155, v167, v199, v155
	v_fma_f32 v134, v134, v170, v156
	v_fma_f32 v135, v135, v171, v157
	s_mov_b32 s0, 0xbfb8aa3b
	v_fma_f32 v134, v104, v162, v134
	v_fma_f32 v135, v105, v163, v135
	v_mul_f32 v104, v154, s0
	v_mul_f32 v105, v155, s0
	v_fma_f32 v42, v162, v194, v42
	v_fma_f32 v43, v163, v195, v43
	v_exp_f32_e32 v104, v104
	v_exp_f32_e32 v105, v105
	v_mul_f32 v42, v154, v42
	v_mul_f32 v43, v155, v43
	v_fma_f32 v118, v118, v166, v160
	v_fma_f32 v119, v119, v167, v161
	v_mul_f32 v96, v150, v96
	v_mul_f32 v97, v151, v97
	v_add_f32 v104, v104, 1.0
	v_add_f32 v105, v105, 1.0
	v_mov_b32_dpp v44, v152 row_shl:1 row_mask:0xf bank_mask:0xf
	v_rcp_f32_e32 v104, v104
	v_rcp_f32_e32 v105, v105
	v_mov_b32_dpp v45, v153 row_shl:1 row_mask:0xf bank_mask:0xf
	v_fma_f32 v44, v184, v44, v192
	v_fma_f32 v45, v185, v45, v193
	v_mov_b32_dpp v200, v132 row_shr:1 row_mask:0xf bank_mask:0xf
	v_mul_f32 v42, v42, v104
	v_mul_f32 v43, v43, v105
	v_mul_f32 v104, v150, s0
	v_mul_f32 v105, v151, s0
	v_mov_b32_dpp v201, v133 row_shr:1 row_mask:0xf bank_mask:0xf
	v_exp_f32_e32 v104, v104
	v_exp_f32_e32 v105, v105
	v_fma_f32 v44, v132, v176, v44
	v_fma_f32 v45, v133, v177, v45
	v_mov_b32_dpp v246, v144 row_shl:1 row_mask:0xf bank_mask:0xf
	v_mov_b32_dpp v247, v145 row_shl:1 row_mask:0xf bank_mask:0xf
	v_add_f32 v104, v104, 1.0
	v_add_f32 v105, v105, 1.0
	v_fma_f32 v44, v54, v168, v44
	v_fma_f32 v45, v55, v169, v45
	v_rcp_f32_e32 v104, v104
	v_rcp_f32_e32 v105, v105
	v_mov_b32_dpp v196, v136 row_shr:1 row_mask:0xf bank_mask:0xf
	v_mov_b32_dpp v197, v137 row_shr:1 row_mask:0xf bank_mask:0xf
	s_and_b64 vcc, exec, s[8:9]
	v_mul_f32 v96, v96, v104
	v_mul_f32 v97, v97, v105
	v_mul_f32 v104, v118, s0
	v_mul_f32 v105, v119, s0
	v_mul_f32 v118, v118, v142
	v_mul_f32 v119, v119, v143
	v_exp_f32_e32 v104, v104
	v_exp_f32_e32 v105, v105
	v_fma_f32 v142, v132, v184, v192
	v_fma_f32 v143, v133, v185, v193
	v_fma_f32 v132, v56, v180, v188
	v_fma_f32 v133, v57, v181, v189
	v_fma_f32 v142, v54, v176, v142
	v_fma_f32 v143, v55, v177, v143
	v_add_f32 v104, v104, 1.0
	v_add_f32 v105, v105, 1.0
	v_fma_f32 v132, v158, v172, v132
	v_fma_f32 v133, v159, v173, v133
	v_rcp_f32_e32 v104, v104
	v_rcp_f32_e32 v105, v105
	v_fma_f32 v132, v144, v164, v132
	v_fma_f32 v133, v145, v165, v133
	v_mov_b32_e32 v103, 0
	v_mov_b32_e32 v170, 0
	v_mul_f32 v104, v118, v104
	v_mul_f32 v105, v119, v105
	v_mul_f32 v118, v130, s0
;     __device__ __forceinline__ void operator()(const f32x4 (&acc)[2][2][4][2], const Unit& u, int wr, int wc, int fr_, int fq_) const {
;     ...
;                 for (int h = 0; h < 2; ++h) {
;                     typedef float f32x2 __attribute__((ext_vector_type(2)));
;     ...
;                     const f32x2 g0 = PAIR(z[ai][0][0][n]), g1 = PAIR(z[ai][0][1][n]), g2 = PAIR(z[ai][0][2][n]), g3 = PAIR(z[ai][0][3][n]);
;                     const f32x2 u0 = PAIR(z[ai][1][0][n]), u1 = PAIR(z[ai][1][1][n]), u2 = PAIR(z[ai][1][2][n]), u3 = PAIR(z[ai][1][3][n]);
;                     const f32x2 pBg2 = PAIR(pBg), nBg2 = PAIR(nBg), pBu2 = PAIR(pBu), nBu2 = PAIR(nBu);
;                     f32x2 pg, ng, pu, nu;
;                     pg.x = dpp_shr1(pBg2.x, g3.x); pg.y = dpp_shr1(pBg2.y, g3.y); ng.x = dpp_shl1(nBg2.x, g0.x); ng.y = dpp_shl1(nBg2.y, g0.y);
;                     pu.x = dpp_shr1(pBu2.x, u3.x); pu.y = dpp_shr1(pBu2.y, u3.y); nu.x = dpp_shl1(nBu2.x, u0.x); nu.y = dpp_shl1(nBu2.y, u0.y);
;                     const f32x2 A0 = PAIR(w0g), A1 = PAIR(w1g), A2 = PAIR(w2g), AB = PAIR(bg), C0 = PAIR(w0u), C1 = PAIR(w1u), C2 = PAIR(w2u), CB = PAIR(bu);
;                     f32x2 G[4], U[4];
;                     G[0] = A0 * pg + (A1 * g0 + (A2 * g1 + AB)); G[1] = A0 * g0 + (A1 * g1 + (A2 * g2 + AB)); G[2] = A0 * g1 + (A1 * g2 + (A2 * g3 + AB)); G[3] = A0 * g2 + (A1 * g3 + (A2 * ng + AB));
;                     U[0] = C0 * pu + (C1 * u0 + (C2 * u1 + CB)); U[1] = C0 * u0 + (C1 * u1 + (C2 * u2 + CB)); U[2] = C0 * u1 + (C1 * u2 + (C2 * u3 + CB)); U[3] = C0 * u2 + (C1 * u3 + (C2 * nu + CB));
; #pragma unroll
;                     for (int m = 0; m < 4; ++m) {
;                         const f32x2 t = G[m] * (-1.4426950408889634f);
;                         f32x2 e; e.x = __builtin_amdgcn_exp2f(t.x); e.y = __builtin_amdgcn_exp2f(t.y);
;                         const f32x2 d = e + 1.0f;
;                         f32x2 r; r.x = __builtin_amdgcn_rcpf(d.x); r.y = __builtin_amdgcn_rcpf(d.y);
;                         const f32x2 q = (G[m] * U[m]) * r;
;                         o[m][2 * h] = q.x; o[m][2 * h + 1] = q.y;
;                     }
;     ...
;                 }
; #pragma unroll
;                 for (int m = 0; m < 4; ++m) { ow[m][2 * n] = cvt_pk_bf16(o[m][0], o[m][1]); ow[m][2 * n + 1] = cvt_pk_bf16(o[m][2], o[m][3]); }
;             }
; #pragma unroll
	v_mul_f32 v119, v131, s0
	v_mul_f32 v130, v130, v134
	v_mul_f32 v131, v131, v135
	v_exp_f32_e32 v118, v118
	v_exp_f32_e32 v119, v119
	v_fma_f32 v134, v54, v184, v192
	v_fma_f32 v135, v55, v185, v193
	v_fma_f32 v54, v158, v180, v188
	v_fma_f32 v55, v159, v181, v189
	v_fma_f32 v134, v120, v176, v134
	v_fma_f32 v135, v121, v177, v135
	v_add_f32 v118, v118, 1.0
	v_add_f32 v119, v119, 1.0
	v_fma_f32 v54, v144, v172, v54
	v_fma_f32 v55, v145, v173, v55
	v_rcp_f32_e32 v118, v118
	v_rcp_f32_e32 v119, v119
	v_fma_f32 v144, v180, v246, v188
	v_fma_f32 v145, v181, v247, v189
	v_fma_f32 v134, v152, v168, v134
	v_fma_f32 v135, v153, v169, v135
	v_fma_f32 v54, v164, v196, v54
	v_fma_f32 v55, v165, v197, v55
	v_mul_f32 v130, v130, v118
	v_mul_f32 v131, v131, v119
	v_fma_f32 v118, v120, v184, v192
	v_fma_f32 v119, v121, v185, v193
	v_fma_f32 v120, v120, v168, v142
	v_fma_f32 v121, v121, v169, v143
	v_fma_f32 v118, v152, v176, v118
	v_fma_f32 v119, v153, v177, v119
	v_fma_f32 v142, v136, v180, v188
	v_fma_f32 v143, v137, v181, v189
	v_fma_f32 v118, v168, v200, v118
	v_fma_f32 v119, v169, v201, v119
	v_fma_f32 v136, v136, v172, v144
	v_fma_f32 v137, v137, v173, v145
	v_fma_f32 v142, v56, v172, v142
	v_fma_f32 v143, v57, v173, v143
	v_fma_f32 v56, v56, v164, v136
	v_fma_f32 v57, v57, v165, v137
	v_mul_f32 v136, v118, s0
	v_mul_f32 v137, v119, s0
	v_mul_f32 v54, v118, v54
	v_mul_f32 v55, v119, v55
	v_mul_f32 v118, v134, s0
	v_mul_f32 v119, v135, s0
	v_mul_f32 v132, v134, v132
	v_mul_f32 v133, v135, v133
	v_exp_f32_e32 v118, v118
	v_exp_f32_e32 v119, v119
	v_fma_f32 v142, v158, v164, v142
	v_fma_f32 v143, v159, v165, v143
	v_exp_f32_e32 v136, v136
	v_exp_f32_e32 v137, v137
	v_add_f32 v118, v118, 1.0
	v_add_f32 v119, v119, 1.0
	v_mov_b32_e32 v171, 0
	v_rcp_f32_e32 v118, v118
	v_rcp_f32_e32 v119, v119
	v_add_f32 v136, v136, 1.0
	v_add_f32 v137, v137, 1.0
	v_mov_b32_e32 v172, 0
	v_rcp_f32_e32 v136, v136
	v_mul_f32 v132, v132, v118
	v_mul_f32 v133, v133, v119
	v_mul_f32 v118, v120, s0
	v_mul_f32 v119, v121, s0
	v_mul_f32 v120, v120, v142
	v_mul_f32 v121, v121, v143
	v_exp_f32_e32 v118, v118
	v_exp_f32_e32 v119, v119
	v_rcp_f32_e32 v137, v137
	v_mov_b32_e32 v173, 0
	v_add_f32 v118, v118, 1.0
	v_add_f32 v119, v119, 1.0
	s_nop 0
	v_rcp_f32_e32 v118, v118
	v_rcp_f32_e32 v119, v119
	v_mul_f32 v54, v54, v136
	v_mul_f32 v55, v55, v137
	v_mul_f32 v120, v120, v118
	v_mul_f32 v121, v121, v119
	v_mul_f32 v118, v44, s0
	v_mul_f32 v119, v45, s0
	v_mul_f32 v44, v44, v56
	v_mul_f32 v45, v45, v57
	v_exp_f32_e32 v118, v118
	v_exp_f32_e32 v119, v119
	s_nop 0
	v_add_f32 v118, v118, 1.0
	v_add_f32 v119, v119, 1.0
	s_nop 0
	v_rcp_f32_e32 v118, v118
	v_rcp_f32_e32 v119, v119
	s_nop 0
	v_mul_f32 v44, v44, v118
	v_mul_f32 v45, v45, v119
	v_cvt_pk_bf16_f32 v118, v42, v43
	v_cvt_pk_bf16_f32 v119, v54, v55
	v_cvt_pk_bf16_f32 v96, v96, v97
	v_cvt_pk_bf16_f32 v97, v132, v133
	v_cvt_pk_bf16_f32 v54, v104, v105
	v_cvt_pk_bf16_f32 v55, v120, v121
	v_cvt_pk_bf16_f32 v42, v130, v131
	s_nop 0
	v_cvt_pk_bf16_f32 v43, v44, v45
	v_or_b32_e32 v44, 4, v236
	v_ashrrev_i32_e32 v45, 31, v44
	v_lshlrev_b64 v[44:45], 2, v[44:45]
	v_lshl_add_u64 v[174:175], s[18:19], 0, v[44:45]
	v_lshl_add_u64 v[176:177], s[50:51], 0, v[44:45]
	v_lshl_add_u64 v[178:179], s[44:45], 0, v[44:45]
	v_lshl_add_u64 v[180:181], s[20:21], 0, v[44:45]
	v_lshl_add_u64 v[182:183], s[42:43], 0, v[44:45]
	v_lshl_add_u64 v[184:185], s[48:49], 0, v[44:45]
	global_load_dwordx4 v[130:133], v[78:79], off offset:16
	global_load_dwordx4 v[142:145], v[174:175], off
	global_load_dwordx4 v[154:157], v[176:177], off
	global_load_dwordx4 v[158:161], v[222:223], off offset:16
	global_load_dwordx4 v[134:137], v[178:179], off
	global_load_dwordx4 v[150:153], v[180:181], off
	global_load_dwordx4 v[162:165], v[182:183], off
	global_load_dwordx4 v[166:169], v[184:185], off
	v_mov_b32_e32 v104, 0
	v_mov_b32_e32 v105, 0
	s_cbranch_vccnz .LBB0_105
	ds_read_b128 v[170:173], v94 offset:272
	ds_read_b128 v[102:105], v94 offset:304
.LBB0_105:
	v_cvt_f32_i32_e32 v33, v33
	v_cvt_f32_i32_e32 v32, v32
	v_cvt_f32_i32_e32 v31, v31
	v_cvt_f32_i32_e32 v30, v30
	v_cvt_f32_i32_e32 v27, v27
	v_cvt_f32_i32_e32 v26, v26
	v_mov_b32_e32 v44, v238
	v_mov_b32_e32 v45, v238
	v_cvt_f32_i32_e32 v29, v29
	v_cvt_f32_i32_e32 v28, v28
	v_mov_b32_e32 v239, v238
	v_mul_f32 v56, v20, v44
	v_mul_f32 v57, v21, v45
	v_mul_f32 v120, v18, v238
	v_mul_f32 v121, v19, v239
	v_mul_f32 v56, v56, v32
	v_mul_f32 v57, v57, v33
	v_mul_f32 v32, v22, v238
	v_mul_f32 v33, v23, v239
	v_readlane_b32 s0, v255, 0
	v_mul_f32 v120, v120, v30
	v_mul_f32 v121, v121, v31
	v_mul_f32 v30, v24, v44
	v_mul_f32 v31, v25, v45
	v_mul_f32 v186, v32, v26
	v_mul_f32 v187, v33, v27
	v_add_u32_e32 v26, s0, v94
	v_readlane_b32 s0, v255, 1
	v_mul_f32 v44, v30, v28
	v_mul_f32 v45, v31, v29
	ds_read_b128 v[26:29], v26
	v_add_u32_e32 v30, s0, v94
	ds_read_b128 v[30:33], v30
	s_waitcnt vmcnt(4)
	v_fma_f32 v188, v110, v154, v158
	v_fma_f32 v189, v111, v155, v159
	s_waitcnt lgkmcnt(3)
	v_mov_b32_dpp v170, v58 row_shr:1 row_mask:0xf bank_mask:0xf
	v_mov_b32_dpp v171, v59 row_shr:1 row_mask:0xf bank_mask:0xf
	v_fma_f32 v188, v146, v142, v188
	v_fma_f32 v189, v147, v143, v189
	s_waitcnt lgkmcnt(1)
	v_mov_b32_dpp v26, v146 row_shl:1 row_mask:0xf bank_mask:0xf
	v_mov_b32_dpp v27, v147 row_shl:1 row_mask:0xf bank_mask:0xf
	v_fma_f32 v170, v130, v170, v188
	v_fma_f32 v171, v131, v171, v189
	v_fma_f32 v188, v120, v154, v158
	v_fma_f32 v189, v121, v155, v159
	s_waitcnt lgkmcnt(0)
; __device__ __forceinline__ float dpp_shr1(float old, float v) { return __builtin_bit_cast(float, __builtin_amdgcn_update_dpp(__builtin_bit_cast(int, old), __builtin_bit_cast(int, v), 0x111, 0xf, 0xf, false)); }
;     __device__ __forceinline__ void operator()(const f32x4 (&acc)[2][2][4][2], const Unit& u, int wr, int wc, int fr_, int fq_) const {
;     ...
;                 for (int h = 0; h < 2; ++h) {
;                     typedef float f32x2 __attribute__((ext_vector_type(2)));
;     ...
;                     const f32x2 g0 = PAIR(z[ai][0][0][n]), g1 = PAIR(z[ai][0][1][n]), g2 = PAIR(z[ai][0][2][n]), g3 = PAIR(z[ai][0][3][n]);
;                     const f32x2 u0 = PAIR(z[ai][1][0][n]), u1 = PAIR(z[ai][1][1][n]), u2 = PAIR(z[ai][1][2][n]), u3 = PAIR(z[ai][1][3][n]);
;                     const f32x2 pBg2 = PAIR(pBg), nBg2 = PAIR(nBg), pBu2 = PAIR(pBu), nBu2 = PAIR(nBu);
;                     f32x2 pg, ng, pu, nu;
;                     pg.x = dpp_shr1(pBg2.x, g3.x); pg.y = dpp_shr1(pBg2.y, g3.y); ng.x = dpp_shl1(nBg2.x, g0.x); ng.y = dpp_shl1(nBg2.y, g0.y);
;                     pu.x = dpp_shr1(pBu2.x, u3.x); pu.y = dpp_shr1(pBu2.y, u3.y); nu.x = dpp_shl1(nBu2.x, u0.x); nu.y = dpp_shl1(nBu2.y, u0.y);
;                     const f32x2 A0 = PAIR(w0g), A1 = PAIR(w1g), A2 = PAIR(w2g), AB = PAIR(bg), C0 = PAIR(w0u), C1 = PAIR(w1u), C2 = PAIR(w2u), CB = PAIR(bu);
;                     f32x2 G[4], U[4];
;                     G[0] = A0 * pg + (A1 * g0 + (A2 * g1 + AB)); G[1] = A0 * g0 + (A1 * g1 + (A2 * g2 + AB)); G[2] = A0 * g1 + (A1 * g2 + (A2 * g3 + AB)); G[3] = A0 * g2 + (A1 * g3 + (A2 * ng + AB));
;                     U[0] = C0 * pu + (C1 * u0 + (C2 * u1 + CB)); U[1] = C0 * u0 + (C1 * u1 + (C2 * u2 + CB)); U[2] = C0 * u1 + (C1 * u2 + (C2 * u3 + CB)); U[3] = C0 * u2 + (C1 * u3 + (C2 * nu + CB));
; #pragma unroll
;                     for (int m = 0; m < 4; ++m) {
;                         const f32x2 t = G[m] * (-1.4426950408889634f);
;                         f32x2 e; e.x = __builtin_amdgcn_exp2f(t.x); e.y = __builtin_amdgcn_exp2f(t.y);
;                         const f32x2 d = e + 1.0f;
;                         f32x2 r; r.x = __builtin_amdgcn_rcpf(d.x); r.y = __builtin_amdgcn_rcpf(d.y);
;                         const f32x2 q = (G[m] * U[m]) * r;
;                         o[m][2 * h] = q.x; o[m][2 * h + 1] = q.y;
;                     }
	v_mov_b32_dpp v30, v138 row_shl:1 row_mask:0xf bank_mask:0xf
	v_mov_b32_dpp v31, v139 row_shl:1 row_mask:0xf bank_mask:0xf
	v_fma_f32 v188, v110, v142, v188
	v_fma_f32 v189, v111, v143, v189
	v_fma_f32 v26, v154, v26, v158
	v_fma_f32 v27, v155, v27, v159
	v_fma_f32 v146, v146, v130, v188
	v_fma_f32 v147, v147, v131, v189
	v_fma_f32 v188, v58, v154, v158
	v_fma_f32 v189, v59, v155, v159
	v_fma_f32 v26, v58, v142, v26
	v_fma_f32 v27, v59, v143, v27
	s_waitcnt vmcnt(0)
	v_fma_f32 v30, v162, v30, v166
	v_fma_f32 v31, v163, v31, v167
	s_mov_b32 s0, 0xbfb8aa3b
	v_mov_b32_dpp v102, v62 row_shr:1 row_mask:0xf bank_mask:0xf
	v_mov_b32_dpp v103, v63 row_shr:1 row_mask:0xf bank_mask:0xf
	v_fma_f32 v188, v120, v142, v188
	v_fma_f32 v189, v121, v143, v189
	v_fma_f32 v26, v120, v130, v26
	v_fma_f32 v27, v121, v131, v27
	v_fma_f32 v120, v62, v162, v166
	v_fma_f32 v121, v63, v163, v167
	v_fma_f32 v30, v62, v150, v30
	v_fma_f32 v31, v63, v151, v31
	v_mul_f32 v62, v170, s0
	v_mul_f32 v63, v171, s0
	v_fma_f32 v58, v98, v162, v166
	v_fma_f32 v59, v99, v163, v167
	v_exp_f32_e32 v62, v62
	v_exp_f32_e32 v63, v63
	v_fma_f32 v58, v138, v150, v58
	v_fma_f32 v59, v139, v151, v59
	v_fma_f32 v110, v110, v130, v188
	v_fma_f32 v111, v111, v131, v189
	v_fma_f32 v58, v134, v102, v58
	v_fma_f32 v59, v135, v103, v59
	v_add_f32 v62, v62, 1.0
	v_add_f32 v63, v63, 1.0
	v_fma_f32 v102, v186, v162, v166
	v_fma_f32 v103, v187, v163, v167
	v_rcp_f32_e32 v62, v62
	v_rcp_f32_e32 v63, v63
	v_fma_f32 v102, v98, v150, v102
	v_fma_f32 v103, v99, v151, v103
	v_fma_f32 v120, v186, v150, v120
	v_fma_f32 v121, v187, v151, v121
	v_fma_f32 v102, v138, v134, v102
	v_fma_f32 v103, v139, v135, v103
	v_mul_f32 v58, v170, v58
	v_mul_f32 v59, v171, v59
	v_fma_f32 v98, v98, v134, v120
	v_fma_f32 v99, v99, v135, v121
	v_mul_f32 v120, v146, s0
	v_mul_f32 v121, v147, s0
	v_mul_f32 v58, v58, v62
	v_mul_f32 v59, v59, v63
	v_mul_f32 v62, v146, v102
	v_mul_f32 v63, v147, v103
	v_mul_f32 v102, v110, s0
	v_mul_f32 v103, v111, s0
	v_exp_f32_e32 v120, v120
	v_exp_f32_e32 v121, v121
	v_exp_f32_e32 v102, v102
	v_exp_f32_e32 v103, v103
	v_mov_b32_dpp v28, v148 row_shl:1 row_mask:0xf bank_mask:0xf
	v_add_f32 v120, v120, 1.0
	v_add_f32 v121, v121, 1.0
	v_mov_b32_dpp v29, v149 row_shl:1 row_mask:0xf bank_mask:0xf
	v_add_f32 v102, v102, 1.0
	v_add_f32 v103, v103, 1.0
	v_rcp_f32_e32 v120, v120
	v_rcp_f32_e32 v121, v121
	v_rcp_f32_e32 v102, v102
	v_rcp_f32_e32 v103, v103
	v_fma_f32 v28, v156, v28, v160
	v_fma_f32 v29, v157, v29, v161
	v_fma_f32 v30, v186, v134, v30
	v_fma_f32 v31, v187, v135, v31
	v_mul_f32 v98, v110, v98
	v_mul_f32 v99, v111, v99
	v_fma_f32 v110, v60, v156, v160
	v_fma_f32 v111, v61, v157, v161
	v_fma_f32 v28, v60, v144, v28
	v_fma_f32 v29, v61, v145, v29
	v_mul_f32 v62, v62, v120
	v_mul_f32 v63, v63, v121
	v_mul_f32 v120, v26, s0
	v_mul_f32 v121, v27, s0
	v_mul_f32 v102, v98, v102
	v_mul_f32 v103, v99, v103
	v_mul_f32 v26, v26, v30
	v_mul_f32 v27, v27, v31
	v_mov_b32_dpp v32, v140 row_shl:1 row_mask:0xf bank_mask:0xf
	v_mov_b32_dpp v33, v141 row_shl:1 row_mask:0xf bank_mask:0xf
	v_fma_f32 v30, v112, v156, v160
	v_fma_f32 v31, v113, v157, v161
	v_fma_f32 v98, v56, v156, v160
	v_fma_f32 v99, v57, v157, v161
	v_fma_f32 v110, v56, v144, v110
	v_fma_f32 v111, v57, v145, v111
	v_fma_f32 v28, v56, v132, v28
	v_fma_f32 v29, v57, v133, v29
	v_fma_f32 v56, v100, v164, v168
	v_fma_f32 v57, v101, v165, v169
	v_mov_b32_dpp v172, v60 row_shr:1 row_mask:0xf bank_mask:0xf
	v_mov_b32_dpp v173, v61 row_shr:1 row_mask:0xf bank_mask:0xf
	v_mov_b32_dpp v104, v64 row_shr:1 row_mask:0xf bank_mask:0xf
	v_mov_b32_dpp v105, v65 row_shr:1 row_mask:0xf bank_mask:0xf
	v_fma_f32 v30, v148, v144, v30
	v_fma_f32 v31, v149, v145, v31
	v_fma_f32 v56, v140, v152, v56
	v_fma_f32 v57, v141, v153, v57
	v_fma_f32 v32, v164, v32, v168
	v_fma_f32 v33, v165, v33, v169
	v_fma_f32 v30, v132, v172, v30
	v_fma_f32 v31, v133, v173, v31
	v_fma_f32 v56, v136, v104, v56
	v_fma_f32 v57, v137, v105, v57
	v_fma_f32 v104, v64, v164, v168
	v_fma_f32 v105, v65, v165, v169
	v_fma_f32 v32, v64, v152, v32
	v_fma_f32 v33, v65, v153, v33
	v_fma_f32 v60, v44, v164, v168
	v_fma_f32 v61, v45, v165, v169
	v_fma_f32 v104, v44, v152, v104
	v_fma_f32 v105, v45, v153, v105
	v_fma_f32 v32, v44, v136, v32
	v_fma_f32 v33, v45, v137, v33
	v_mul_f32 v44, v30, s0
	v_mul_f32 v45, v31, s0
	v_fma_f32 v98, v112, v144, v98
	v_fma_f32 v99, v113, v145, v99
	v_exp_f32_e32 v44, v44
	v_exp_f32_e32 v45, v45
	v_fma_f32 v98, v148, v132, v98
	v_fma_f32 v99, v149, v133, v99
	v_fma_f32 v60, v100, v152, v60
	v_fma_f32 v61, v101, v153, v61
	v_fma_f32 v110, v112, v132, v110
	v_fma_f32 v111, v113, v133, v111
	v_add_f32 v44, v44, 1.0
	v_add_f32 v45, v45, 1.0
	v_fma_f32 v60, v140, v136, v60
	v_fma_f32 v61, v141, v137, v61
	v_rcp_f32_e32 v44, v44
	v_rcp_f32_e32 v45, v45
	v_mul_f32 v64, v98, s0
	v_mul_f32 v65, v99, s0
	v_mul_f32 v30, v30, v56
	v_mul_f32 v31, v31, v57
	v_exp_f32_e32 v120, v120
	v_exp_f32_e32 v121, v121
	v_exp_f32_e32 v64, v64
	v_exp_f32_e32 v65, v65
	v_mul_f32 v30, v30, v44
	v_mul_f32 v31, v31, v45
	v_mul_f32 v44, v98, v60
	v_mul_f32 v45, v99, v61
	v_mul_f32 v56, v110, s0
	v_mul_f32 v57, v111, s0
	v_mul_f32 v60, v28, s0
	v_mul_f32 v61, v29, s0
	v_exp_f32_e32 v56, v56
	v_exp_f32_e32 v57, v57
	v_exp_f32_e32 v60, v60
	v_exp_f32_e32 v61, v61
	v_add_f32 v120, v120, 1.0
	v_add_f32 v121, v121, 1.0
	v_add_f32 v64, v64, 1.0
	v_add_f32 v65, v65, 1.0
	v_rcp_f32_e32 v120, v120
	v_rcp_f32_e32 v121, v121
	v_rcp_f32_e32 v64, v64
	v_rcp_f32_e32 v65, v65
	v_add_f32 v56, v56, 1.0
	v_add_f32 v57, v57, 1.0
	v_add_f32 v60, v60, 1.0
	v_add_f32 v61, v61, 1.0
	v_rcp_f32_e32 v56, v56
	v_rcp_f32_e32 v57, v57
; __device__ __forceinline__ unsigned cvt_pk_bf16(float lo, float hi) { unsigned r; asm volatile("v_cvt_pk_bf16_f32 %0, %1, %2" : "=v"(r) : "v"(lo), "v"(hi)); return r; }
; __device__ __forceinline__ float rstd2048(const stat_t* rs, int row) { return rsqrtf((float)rs[row] * (STAT_INV / 2048.0f) + NORM_EPS); }
;     __device__ __forceinline__ void operator()(const f32x4 (&acc)[2][2][4][2], const Unit& u, int wr, int wc, int fr_, int fq_) const {
;     ...
;             for (int m = 0; m < 4; ++m) { const float r = rstd2048(rs, rowb + ai * HALF + m) * sx[rowb + ai * HALF + m];
; #pragma unroll
;                 for (int bj = 0; bj < 2; ++bj)
; #pragma unroll
;                     for (int n = 0; n < 2; ++n) { typedef int i32x4 __attribute__((ext_vector_type(4)));
;                         z[ai][bj][m][n] = __builtin_convertvector(__builtin_bit_cast(i32x4, acc[ai][bj][m][n]), f32x4) * (swv[bj][n] * r); } }
;     ...
; #pragma unroll
;                 for (int m = 0; m < 4; ++m) { ow[m][2 * n] = cvt_pk_bf16(o[m][0], o[m][1]); ow[m][2 * n + 1] = cvt_pk_bf16(o[m][2], o[m][3]); }
;             }
; #pragma unroll
;             for (int m = 0; m < 4; ++m) { u32x4 w; w.x = ow[m][0]; w.y = ow[m][1]; w.z = ow[m][2]; w.w = ow[m][3];
;                 *(u32x4*)(ACT + (size_t)(rowb + ai * HALF + m) * DFF_ + ch0) = w; }
	v_rcp_f32_e32 v60, v60
	v_rcp_f32_e32 v61, v61
	v_fma_f32 v100, v100, v136, v104
	v_fma_f32 v101, v101, v137, v105
	v_readlane_b32 s0, v252, 18
	v_mul_f32 v26, v26, v120
	v_mul_f32 v27, v27, v121
	v_mul_f32 v44, v44, v64
	v_mul_f32 v45, v45, v65
	v_mul_f32 v64, v110, v100
	v_mul_f32 v65, v111, v101
	v_mul_f32 v28, v28, v32
	v_mul_f32 v29, v29, v33
	v_readlane_b32 s1, v252, 19
	v_mul_f32 v64, v64, v56
	v_mul_f32 v65, v65, v57
	v_mul_f32 v28, v28, v60
	v_mul_f32 v29, v29, v61
	v_cvt_pk_bf16_f32 v120, v58, v59
	v_cvt_pk_bf16_f32 v121, v30, v31
	v_cvt_pk_bf16_f32 v98, v62, v63
	v_cvt_pk_bf16_f32 v99, v44, v45
	v_cvt_pk_bf16_f32 v56, v102, v103
	v_cvt_pk_bf16_f32 v57, v64, v65
	v_cvt_pk_bf16_f32 v44, v26, v27
	v_mov_b64_e32 v[26:27], s[0:1]
	s_movk_i32 s4, 0x2c00
	v_cvt_pk_bf16_f32 v45, v28, v29
	v_mad_i64_i32 v[28:29], s[0:1], v220, s4, v[26:27]
	v_lshlrev_b64 v[142:143], 1, v[236:237]
	v_or_b32_e32 v190, 1, v220
	v_lshl_add_u64 v[28:29], v[28:29], 0, v[142:143]
	global_store_dwordx4 v[28:29], v[118:121], off
	v_mad_i64_i32 v[28:29], s[0:1], v190, s4, v[26:27]
	v_or_b32_e32 v191, 2, v220
	v_or_b32_e32 v192, 3, v220
	v_lshl_add_u64 v[28:29], v[28:29], 0, v[142:143]
	global_store_dwordx4 v[28:29], v[96:99], off
	v_mad_i64_i32 v[28:29], s[0:1], v191, s4, v[26:27]
	v_mad_i64_i32 v[26:27], s[0:1], v192, s4, v[26:27]
	v_lshl_add_u64 v[28:29], v[28:29], 0, v[142:143]
	v_lshl_add_u64 v[26:27], v[26:27], 0, v[142:143]
	global_store_dwordx4 v[28:29], v[54:57], off
	global_store_dwordx4 v[26:27], v[42:45], off
	global_load_dwordx4 v[62:65], v[78:79], off
	global_load_dwordx4 v[96:99], v[224:225], off
	global_load_dwordx4 v[100:103], v[226:227], off
	global_load_dwordx4 v[110:113], v[222:223], off
	global_load_dwordx4 v[28:31], v[228:229], off
	global_load_dwordx4 v[42:45], v[230:231], off
	global_load_dwordx4 v[54:57], v[232:233], off
	global_load_dwordx4 v[58:61], v[234:235], off
	v_readlane_b32 s0, v255, 12
	v_add_u32_e32 v26, 0x1100, v94
	v_add_u32_e32 v104, 0x1120, v94
	v_add_u32_e32 v33, s0, v205
	v_add_u32_e32 v27, 0x100, v33
	v_add_u32_e32 v32, 0x120, v33
	v_cndmask_b32_e64 v26, v26, v27, s[46:47]
	v_cndmask_b32_e64 v32, v104, v32, s[46:47]
	ds_read_b128 v[134:137], v26
	ds_read_b128 v[118:121], v32
	v_readlane_b32 s4, v254, 44
	v_readlane_b32 s5, v254, 45
	v_mov_b32_e32 v26, 0
	s_andn2_b64 vcc, exec, s[4:5]
	v_cndmask_b32_e64 v27, 0, 1, s[4:5]
	v_cmp_ne_u32_e64 s[0:1], 1, v27
	v_mov_b32_e32 v138, 0
	v_mov_b32_e32 v139, 0
	v_mov_b32_e32 v140, 0
	v_mov_b32_e32 v141, 0
	v_mov_b32_e32 v130, 0
	v_mov_b32_e32 v131, 0
	v_mov_b32_e32 v132, 0
	v_mov_b32_e32 v133, 0
	v_mov_b32_e32 v244, v206
	v_mov_b32_e32 v246, v202
	v_mov_b32_e32 v202, v207
	v_mov_b32_e32 v245, v221
	s_cbranch_vccnz .LBB0_107
	ds_read_b128 v[138:141], v33 offset:4096
	ds_read_b128 v[130:133], v33 offset:4128
.LBB0_107:
	v_ffbh_u32_e32 v27, v81
	v_min_u32_e32 v27, 32, v27
	v_lshlrev_b64 v[80:81], v27, v[80:81]
	v_min_u32_e32 v32, 1, v80
	v_or_b32_e32 v32, v81, v32
	v_cvt_f32_u32_e32 v32, v32
	v_sub_u32_e32 v27, 32, v27
	v_cvt_f32_i32_e32 v81, v15
	v_cvt_f32_i32_e32 v80, v14
	v_ldexp_f32 v27, v32, v27
	v_fmamk_f32 v27, v27, 0x2e000000, v204
	v_cmp_gt_f32_e32 vcc, s17, v27
	v_mul_f32_e32 v32, 0x4b800000, v27
	v_cvt_f32_i32_e32 v15, v17
	v_cndmask_b32_e32 v27, v27, v32, vcc
	v_rsq_f32_e32 v27, v27
	v_cvt_f32_i32_e32 v14, v16
	v_cvt_f32_i32_e32 v11, v11
	v_cvt_f32_i32_e32 v10, v10
	v_mul_f32_e32 v32, 0x45800000, v27
	v_cndmask_b32_e32 v27, v27, v32, vcc
	v_mul_f32_e32 v32, v95, v27
	v_cvt_f32_i32_e32 v13, v13
	v_cvt_f32_i32_e32 v12, v12
	v_mul_f32 v16, v38, v32
	v_mul_f32 v17, v39, v32
	v_mul_f32 v38, v40, v32
	v_mul_f32 v39, v41, v32
	v_mul_f32 v34, v34, v32
	v_mul_f32 v35, v35, v32
	v_mul_f32 v14, v38, v14
	v_mul_f32 v15, v39, v15
	v_mul_f32 v38, v16, v80
	v_mul_f32 v39, v17, v81
	v_mul_f32 v16, v36, v32
	v_mul_f32 v17, v37, v32
	s_waitcnt vmcnt(4)
	v_fma_f32 v36, v126, v100, v110
	v_fma_f32 v37, v127, v101, v111
	v_mul_f32 v10, v34, v10
	v_mul_f32 v11, v35, v11
	s_waitcnt lgkmcnt(1)
	v_mov_b32_dpp v138, v106 row_shl:1 row_mask:0xf bank_mask:0xf
	v_mov_b32_dpp v139, v107 row_shl:1 row_mask:0xf bank_mask:0xf
	v_fma_f32 v34, v90, v100, v110
	v_fma_f32 v35, v91, v101, v111
	v_fma_f32 v36, v90, v96, v36
	v_fma_f32 v37, v91, v97, v37
	v_mul_f32 v16, v16, v12
	v_mul_f32 v17, v17, v13
	v_fma_f32 v12, v38, v100, v110
	v_fma_f32 v13, v39, v101, v111
	v_fma_f32 v34, v38, v96, v34
	v_fma_f32 v35, v39, v97, v35
	v_fma_f32 v36, v38, v62, v36
	v_fma_f32 v37, v39, v63, v37
	v_fma_f32 v38, v100, v138, v110
	v_fma_f32 v39, v101, v139, v111
	v_mov_b32_dpp v134, v126 row_shr:1 row_mask:0xf bank_mask:0xf
	v_mov_b32_dpp v135, v127 row_shr:1 row_mask:0xf bank_mask:0xf
	v_fma_f32 v12, v106, v96, v12
	v_fma_f32 v13, v107, v97, v13
	v_fma_f32 v38, v126, v96, v38
	v_fma_f32 v39, v127, v97, v39
	s_waitcnt vmcnt(0)
	v_fma_f32 v80, v122, v54, v58
	v_fma_f32 v81, v123, v55, v59
	s_waitcnt lgkmcnt(0)
;     __device__ __forceinline__ void operator()(const f32x4 (&acc)[2][2][4][2], const Unit& u, int wr, int wc, int fr_, int fq_) const {
;     ...
;                 for (int h = 0; h < 2; ++h) {
;                     typedef float f32x2 __attribute__((ext_vector_type(2)));
;     ...
;                     const f32x2 g0 = PAIR(z[ai][0][0][n]), g1 = PAIR(z[ai][0][1][n]), g2 = PAIR(z[ai][0][2][n]), g3 = PAIR(z[ai][0][3][n]);
;                     const f32x2 u0 = PAIR(z[ai][1][0][n]), u1 = PAIR(z[ai][1][1][n]), u2 = PAIR(z[ai][1][2][n]), u3 = PAIR(z[ai][1][3][n]);
;                     const f32x2 pBg2 = PAIR(pBg), nBg2 = PAIR(nBg), pBu2 = PAIR(pBu), nBu2 = PAIR(nBu);
;                     f32x2 pg, ng, pu, nu;
;                     pg.x = dpp_shr1(pBg2.x, g3.x); pg.y = dpp_shr1(pBg2.y, g3.y); ng.x = dpp_shl1(nBg2.x, g0.x); ng.y = dpp_shl1(nBg2.y, g0.y);
;                     pu.x = dpp_shr1(pBu2.x, u3.x); pu.y = dpp_shr1(pBu2.y, u3.y); nu.x = dpp_shl1(nBu2.x, u0.x); nu.y = dpp_shl1(nBu2.y, u0.y);
;                     const f32x2 A0 = PAIR(w0g), A1 = PAIR(w1g), A2 = PAIR(w2g), AB = PAIR(bg), C0 = PAIR(w0u), C1 = PAIR(w1u), C2 = PAIR(w2u), CB = PAIR(bu);
;                     f32x2 G[4], U[4];
;                     G[0] = A0 * pg + (A1 * g0 + (A2 * g1 + AB)); G[1] = A0 * g0 + (A1 * g1 + (A2 * g2 + AB)); G[2] = A0 * g1 + (A1 * g2 + (A2 * g3 + AB)); G[3] = A0 * g2 + (A1 * g3 + (A2 * ng + AB));
;                     U[0] = C0 * pu + (C1 * u0 + (C2 * u1 + CB)); U[1] = C0 * u0 + (C1 * u1 + (C2 * u2 + CB)); U[2] = C0 * u1 + (C1 * u2 + (C2 * u3 + CB)); U[3] = C0 * u2 + (C1 * u3 + (C2 * nu + CB));
; #pragma unroll
;                     for (int m = 0; m < 4; ++m) {
;                         const f32x2 t = G[m] * (-1.4426950408889634f);
;                         f32x2 e; e.x = __builtin_amdgcn_exp2f(t.x); e.y = __builtin_amdgcn_exp2f(t.y);
;                         const f32x2 d = e + 1.0f;
;                         f32x2 r; r.x = __builtin_amdgcn_rcpf(d.x); r.y = __builtin_amdgcn_rcpf(d.y);
;                         const f32x2 q = (G[m] * U[m]) * r;
;                         o[m][2 * h] = q.x; o[m][2 * h + 1] = q.y;
;                     }
;     ...
;                 }
; #pragma unroll
;                 for (int m = 0; m < 4; ++m) { ow[m][2 * n] = cvt_pk_bf16(o[m][0], o[m][1]); ow[m][2 * n + 1] = cvt_pk_bf16(o[m][2], o[m][3]); }
	v_mov_b32_dpp v130, v114 row_shl:1 row_mask:0xf bank_mask:0xf
	v_mov_b32_dpp v131, v115 row_shl:1 row_mask:0xf bank_mask:0xf
	v_fma_f32 v12, v62, v134, v12
	v_fma_f32 v13, v63, v135, v13
	v_fma_f32 v34, v106, v62, v34
	v_fma_f32 v35, v107, v63, v35
	v_fma_f32 v38, v90, v62, v38
	v_fma_f32 v39, v91, v63, v39
	v_fma_f32 v62, v82, v54, v58
	v_fma_f32 v63, v83, v55, v59
	v_fma_f32 v80, v82, v42, v80
	v_fma_f32 v81, v83, v43, v81
	v_fma_f32 v40, v10, v54, v58
	v_fma_f32 v41, v11, v55, v59
	v_fma_f32 v62, v10, v42, v62
	v_fma_f32 v63, v11, v43, v63
	v_fma_f32 v80, v10, v28, v80
	v_fma_f32 v81, v11, v29, v81
	v_fma_f32 v10, v54, v130, v58
	v_fma_f32 v11, v55, v131, v59
	s_mov_b32 s4, 0xbfb8aa3b
	v_fma_f32 v10, v122, v42, v10
	v_fma_f32 v11, v123, v43, v11
	v_fma_f32 v40, v114, v42, v40
	v_fma_f32 v41, v115, v43, v41
	v_fma_f32 v42, v82, v28, v10
	v_fma_f32 v43, v83, v29, v11
	v_mul_f32 v10, v12, s4
	v_mul_f32 v11, v13, s4
	v_mov_b32_dpp v118, v122 row_shr:1 row_mask:0xf bank_mask:0xf
	v_exp_f32_e32 v10, v10
	v_exp_f32_e32 v11, v11
	v_mov_b32_dpp v119, v123 row_shr:1 row_mask:0xf bank_mask:0xf
	v_fma_f32 v40, v28, v118, v40
	v_fma_f32 v41, v29, v119, v41
	v_fma_f32 v62, v114, v28, v62
	v_fma_f32 v63, v115, v29, v63
	v_add_f32 v10, v10, 1.0
	v_add_f32 v11, v11, 1.0
	v_mul_f32 v12, v12, v40
	v_mul_f32 v13, v13, v41
	v_rcp_f32_e32 v10, v10
	v_rcp_f32_e32 v11, v11
	v_mul_f32 v28, v34, v62
	v_mul_f32 v29, v35, v63
	v_mov_b32_dpp v132, v116 row_shl:1 row_mask:0xf bank_mask:0xf
	v_mov_b32_dpp v133, v117 row_shl:1 row_mask:0xf bank_mask:0xf
	v_mul_f32 v10, v12, v10
	v_mul_f32 v11, v13, v11
	v_mul_f32 v12, v34, s4
	v_mul_f32 v13, v35, s4
	v_mul_f32 v34, v36, v80
	v_mul_f32 v35, v37, v81
	v_exp_f32_e32 v12, v12
	v_exp_f32_e32 v13, v13
	v_mov_b32_dpp v136, v128 row_shr:1 row_mask:0xf bank_mask:0xf
	v_mov_b32_dpp v137, v129 row_shr:1 row_mask:0xf bank_mask:0xf
	v_fma_f32 v54, v84, v56, v60
	v_fma_f32 v55, v85, v57, v61
	v_add_f32 v12, v12, 1.0
	v_add_f32 v13, v13, 1.0
	v_fma_f32 v58, v124, v56, v60
	v_fma_f32 v59, v125, v57, v61
	v_rcp_f32_e32 v12, v12
	v_rcp_f32_e32 v13, v13
	v_mov_b32_dpp v120, v124 row_shr:1 row_mask:0xf bank_mask:0xf
	v_mov_b32_dpp v121, v125 row_shr:1 row_mask:0xf bank_mask:0xf
	v_fma_f32 v54, v16, v44, v54
	v_fma_f32 v55, v17, v45, v55
	v_mul_f32 v12, v28, v12
	v_mul_f32 v13, v29, v13
	v_mul_f32 v28, v36, s4
	v_mul_f32 v29, v37, s4
	v_mul_f32 v36, v38, v42
	v_mul_f32 v37, v39, v43
	v_exp_f32_e32 v28, v28
	v_exp_f32_e32 v29, v29
	v_fma_f32 v42, v16, v56, v60
	v_fma_f32 v43, v17, v57, v61
	v_fma_f32 v56, v56, v132, v60
	v_fma_f32 v57, v57, v133, v61
	v_fma_f32 v42, v116, v44, v42
	v_fma_f32 v43, v117, v45, v43
	v_add_f32 v28, v28, 1.0
	v_add_f32 v29, v29, 1.0
	v_fma_f32 v58, v84, v44, v58
	v_fma_f32 v59, v85, v45, v59
	v_rcp_f32_e32 v28, v28
	v_rcp_f32_e32 v29, v29
	v_fma_f32 v44, v124, v44, v56
	v_fma_f32 v45, v125, v45, v57
	v_fma_f32 v42, v30, v120, v42
	v_fma_f32 v43, v31, v121, v43
	v_fma_f32 v54, v116, v30, v54
	v_fma_f32 v55, v117, v31, v55
	v_mul_f32 v28, v34, v28
	v_mul_f32 v29, v35, v29
	v_mul_f32 v34, v38, s4
	v_mul_f32 v35, v39, s4
	v_fma_f32 v16, v16, v30, v58
	v_fma_f32 v17, v17, v31, v59
	v_exp_f32_e32 v34, v34
	v_exp_f32_e32 v35, v35
	v_fma_f32 v30, v84, v30, v44
	v_fma_f32 v31, v85, v31, v45
	v_fma_f32 v38, v92, v102, v112
	v_fma_f32 v39, v93, v103, v113
	v_fma_f32 v40, v128, v102, v112
	v_fma_f32 v41, v129, v103, v113
	v_add_f32 v34, v34, 1.0
	v_add_f32 v35, v35, 1.0
	v_fma_f32 v38, v14, v98, v38
	v_fma_f32 v39, v15, v99, v39
	v_rcp_f32_e32 v34, v34
	v_rcp_f32_e32 v35, v35
	v_fma_f32 v38, v108, v64, v38
	v_fma_f32 v39, v109, v65, v39
	v_fma_f32 v40, v92, v98, v40
	v_fma_f32 v41, v93, v99, v41
	v_mov_b32_dpp v140, v108 row_shl:1 row_mask:0xf bank_mask:0xf
	v_mul_f32 v36, v36, v34
	v_mul_f32 v37, v37, v35
	v_fma_f32 v34, v14, v102, v112
	v_fma_f32 v35, v15, v103, v113
	v_fma_f32 v14, v14, v64, v40
	v_fma_f32 v15, v15, v65, v41
	v_fma_f32 v34, v108, v98, v34
	v_fma_f32 v35, v109, v99, v35
	v_mov_b32_dpp v141, v109 row_shl:1 row_mask:0xf bank_mask:0xf
	v_fma_f32 v34, v64, v136, v34
	v_fma_f32 v35, v65, v137, v35
	v_fma_f32 v40, v102, v140, v112
	v_fma_f32 v41, v103, v141, v113
	v_mul_f32 v44, v34, s4
	v_mul_f32 v45, v35, s4
	v_mul_f32 v34, v34, v42
	v_mul_f32 v35, v35, v43
	v_exp_f32_e32 v44, v44
	v_exp_f32_e32 v45, v45
	v_fma_f32 v40, v128, v98, v40
	v_fma_f32 v41, v129, v99, v41
	s_and_b64 vcc, exec, s[0:1]
	v_fma_f32 v40, v92, v64, v40
	v_fma_f32 v41, v93, v65, v41
	v_add_f32 v44, v44, 1.0
	v_add_f32 v45, v45, 1.0
	v_mul_f32 v30, v40, v30
	v_mul_f32 v31, v41, v31
	v_rcp_f32_e32 v44, v44
	v_rcp_f32_e32 v45, v45
	v_mov_b32_e32 v27, 0
	v_mov_b32_e32 v98, 0
	v_mov_b32_e32 v99, 0
	v_mul_f32 v42, v34, v44
	v_mul_f32 v43, v35, v45
	v_mul_f32 v34, v38, s4
	v_mul_f32 v35, v39, s4
	v_mul_f32 v38, v38, v54
	v_mul_f32 v39, v39, v55
	v_exp_f32_e32 v34, v34
	v_exp_f32_e32 v35, v35
	v_mov_b32_e32 v100, 0
	v_mov_b32_e32 v101, 0
	v_add_f32 v34, v34, 1.0
	v_add_f32 v35, v35, 1.0
	s_nop 0
	v_rcp_f32_e32 v34, v34
	v_rcp_f32_e32 v35, v35
	s_nop 0
	v_mul_f32 v38, v38, v34
	v_mul_f32 v39, v39, v35
	v_mul_f32 v34, v14, s4
	v_mul_f32 v35, v15, s4
	v_mul_f32 v14, v14, v16
	v_mul_f32 v15, v15, v17
	v_exp_f32_e32 v34, v34
	v_exp_f32_e32 v35, v35
	s_nop 0
	v_add_f32 v34, v34, 1.0
	v_add_f32 v35, v35, 1.0
	s_nop 0
	v_rcp_f32_e32 v34, v34
	v_rcp_f32_e32 v35, v35
	s_nop 0
	v_mul_f32 v16, v14, v34
	v_mul_f32 v17, v15, v35
	v_mul_f32 v14, v40, s4
	v_mul_f32 v15, v41, s4
	v_cvt_pk_bf16_f32 v34, v10, v11
	v_cvt_pk_bf16_f32 v35, v42, v43
	s_mov_b32 s5, s29
	v_exp_f32_e32 v14, v14
	v_exp_f32_e32 v15, v15
	s_nop 0
	v_add_f32 v14, v14, 1.0
	v_add_f32 v15, v15, 1.0
	s_nop 0
	v_rcp_f32_e32 v14, v14
	v_rcp_f32_e32 v15, v15
	s_nop 0
	v_mul_f32 v40, v30, v14
	v_mul_f32 v41, v31, v15
	v_cvt_pk_bf16_f32 v30, v12, v13
	v_cvt_pk_bf16_f32 v31, v38, v39
	v_cvt_pk_bf16_f32 v14, v28, v29
	v_cvt_pk_bf16_f32 v15, v16, v17
	v_cvt_pk_bf16_f32 v10, v36, v37
	s_nop 0
	v_cvt_pk_bf16_f32 v11, v40, v41
	global_load_dwordx4 v[62:65], v[78:79], off offset:16
	s_nop 0
	global_load_dwordx4 v[78:81], v[174:175], off
	global_load_dwordx4 v[82:85], v[176:177], off
	global_load_dwordx4 v[90:93], v[222:223], off offset:16
	global_load_dwordx4 v[36:39], v[178:179], off
	global_load_dwordx4 v[40:43], v[180:181], off
	global_load_dwordx4 v[54:57], v[182:183], off
	global_load_dwordx4 v[58:61], v[184:185], off
	v_add_u32_e32 v12, 0x110, v33
	v_add_u32_e32 v16, 0x1110, v94
	v_add_u32_e32 v13, 0x130, v33
	v_add_u32_e32 v17, 0x1130, v94
	v_cndmask_b32_e64 v12, v16, v12, s[46:47]
	v_cndmask_b32_e64 v13, v17, v13, s[46:47]
	ds_read_b128 v[102:105], v12
	ds_read_b128 v[94:97], v13
	v_mov_b32_e32 v28, 0
	v_mov_b32_e32 v29, 0
	s_cbranch_vccnz .LBB0_109
	ds_read_b128 v[26:29], v33 offset:4112
	ds_read_b128 v[98:101], v33 offset:4144
; __device__ __forceinline__ float dpp_shr1(float old, float v) { return __builtin_bit_cast(float, __builtin_amdgcn_update_dpp(__builtin_bit_cast(int, old), __builtin_bit_cast(int, v), 0x111, 0xf, 0xf, false)); }
; __device__ __forceinline__ float dpp_shl1(float old, float v) { return __builtin_bit_cast(float, __builtin_amdgcn_update_dpp(__builtin_bit_cast(int, old), __builtin_bit_cast(int, v), 0x101, 0xf, 0xf, false)); }
; #define PAIR(v) (h == 0 ? __builtin_shufflevector(v, v, 0, 1) : __builtin_shufflevector(v, v, 2, 3))
;     __device__ __forceinline__ void operator()(const f32x4 (&acc)[2][2][4][2], const Unit& u, int wr, int wc, int fr_, int fq_) const {
;     ...
;                 for (int h = 0; h < 2; ++h) {
;                     typedef float f32x2 __attribute__((ext_vector_type(2)));
;     ...
;                     const f32x2 g0 = PAIR(z[ai][0][0][n]), g1 = PAIR(z[ai][0][1][n]), g2 = PAIR(z[ai][0][2][n]), g3 = PAIR(z[ai][0][3][n]);
;                     const f32x2 u0 = PAIR(z[ai][1][0][n]), u1 = PAIR(z[ai][1][1][n]), u2 = PAIR(z[ai][1][2][n]), u3 = PAIR(z[ai][1][3][n]);
;                     const f32x2 pBg2 = PAIR(pBg), nBg2 = PAIR(nBg), pBu2 = PAIR(pBu), nBu2 = PAIR(nBu);
;                     f32x2 pg, ng, pu, nu;
;                     pg.x = dpp_shr1(pBg2.x, g3.x); pg.y = dpp_shr1(pBg2.y, g3.y); ng.x = dpp_shl1(nBg2.x, g0.x); ng.y = dpp_shl1(nBg2.y, g0.y);
;                     pu.x = dpp_shr1(pBu2.x, u3.x); pu.y = dpp_shr1(pBu2.y, u3.y); nu.x = dpp_shl1(nBu2.x, u0.x); nu.y = dpp_shl1(nBu2.y, u0.y);
;                     const f32x2 A0 = PAIR(w0g), A1 = PAIR(w1g), A2 = PAIR(w2g), AB = PAIR(bg), C0 = PAIR(w0u), C1 = PAIR(w1u), C2 = PAIR(w2u), CB = PAIR(bu);
;                     f32x2 G[4], U[4];
;                     G[0] = A0 * pg + (A1 * g0 + (A2 * g1 + AB)); G[1] = A0 * g0 + (A1 * g1 + (A2 * g2 + AB)); G[2] = A0 * g1 + (A1 * g2 + (A2 * g3 + AB)); G[3] = A0 * g2 + (A1 * g3 + (A2 * ng + AB));
;                     U[0] = C0 * pu + (C1 * u0 + (C2 * u1 + CB)); U[1] = C0 * u0 + (C1 * u1 + (C2 * u2 + CB)); U[2] = C0 * u1 + (C1 * u2 + (C2 * u3 + CB)); U[3] = C0 * u2 + (C1 * u3 + (C2 * nu + CB));
; #pragma unroll
;                     for (int m = 0; m < 4; ++m) {
;                         const f32x2 t = G[m] * (-1.4426950408889634f);
;                         f32x2 e; e.x = __builtin_amdgcn_exp2f(t.x); e.y = __builtin_amdgcn_exp2f(t.y);
.LBB0_109:
	v_cvt_f32_i32_e32 v9, v9
	v_cvt_f32_i32_e32 v8, v8
	v_mov_b32_e32 v12, v32
	v_mov_b32_e32 v13, v32
	v_cvt_f32_i32_e32 v5, v5
	v_cvt_f32_i32_e32 v4, v4
	s_waitcnt lgkmcnt(1)
	v_mov_b32_dpp v26, v46 row_shl:1 row_mask:0xf bank_mask:0xf
	v_mov_b32_dpp v27, v47 row_shl:1 row_mask:0xf bank_mask:0xf
	v_mul_f32 v16, v24, v12
	v_mul_f32 v17, v25, v13
	v_cvt_f32_i32_e32 v7, v7
	v_cvt_f32_i32_e32 v6, v6
	v_mul_f32 v12, v20, v12
	v_mul_f32 v13, v21, v13
	v_mov_b32_e32 v33, v32
	v_mul_f32 v8, v12, v8
	v_mul_f32 v9, v13, v9
	s_waitcnt vmcnt(4)
	v_fma_f32 v12, v82, v26, v90
	v_fma_f32 v13, v83, v27, v91
	v_mul_f32 v4, v16, v4
	v_mul_f32 v5, v17, v5
	v_fma_f32 v12, v66, v78, v12
	v_fma_f32 v13, v67, v79, v13
	v_mul_f32 v16, v18, v32
	v_mul_f32 v17, v19, v33
	v_fma_f32 v12, v86, v62, v12
	v_fma_f32 v13, v87, v63, v13
	s_mov_b32 s0, 0xbfb8aa3b
	v_cvt_f32_i32_e32 v3, v3
	v_cvt_f32_i32_e32 v2, v2
	v_mul_f32 v6, v16, v6
	v_mul_f32 v7, v17, v7
	v_mul_f32 v16, v12, s0
	v_mul_f32 v17, v13, s0
	v_fma_f32 v20, v66, v82, v90
	v_fma_f32 v21, v67, v83, v91
	v_exp_f32_e32 v16, v16
	v_exp_f32_e32 v17, v17
	v_fma_f32 v20, v86, v78, v20
	v_fma_f32 v21, v87, v79, v21
	v_mul_f32 v22, v22, v32
	v_mul_f32 v23, v23, v33
	v_fma_f32 v20, v6, v62, v20
	v_fma_f32 v21, v7, v63, v21
	v_mul_f32 v2, v22, v2
	v_mul_f32 v3, v23, v3
	v_mul_f32 v22, v20, s0
	v_mul_f32 v23, v21, s0
	s_waitcnt lgkmcnt(0)
	v_mov_b32_dpp v98, v50 row_shl:1 row_mask:0xf bank_mask:0xf
	v_mov_b32_dpp v99, v51 row_shl:1 row_mask:0xf bank_mask:0xf
	v_add_f32 v16, v16, 1.0
	v_add_f32 v17, v17, 1.0
	v_exp_f32_e32 v22, v22
	v_exp_f32_e32 v23, v23
	s_waitcnt vmcnt(0)
; __device__ __forceinline__ unsigned cvt_pk_bf16(float lo, float hi) { unsigned r; asm volatile("v_cvt_pk_bf16_f32 %0, %1, %2" : "=v"(r) : "v"(lo), "v"(hi)); return r; }
; #define PAIR(v) (h == 0 ? __builtin_shufflevector(v, v, 0, 1) : __builtin_shufflevector(v, v, 2, 3))
;     __device__ __forceinline__ void operator()(const f32x4 (&acc)[2][2][4][2], const Unit& u, int wr, int wc, int fr_, int fq_) const {
;     ...
;                     const f32x2 A0 = PAIR(w0g), A1 = PAIR(w1g), A2 = PAIR(w2g), AB = PAIR(bg), C0 = PAIR(w0u), C1 = PAIR(w1u), C2 = PAIR(w2u), CB = PAIR(bu);
;                     f32x2 G[4], U[4];
;                     G[0] = A0 * pg + (A1 * g0 + (A2 * g1 + AB)); G[1] = A0 * g0 + (A1 * g1 + (A2 * g2 + AB)); G[2] = A0 * g1 + (A1 * g2 + (A2 * g3 + AB)); G[3] = A0 * g2 + (A1 * g3 + (A2 * ng + AB));
;                     U[0] = C0 * pu + (C1 * u0 + (C2 * u1 + CB)); U[1] = C0 * u0 + (C1 * u1 + (C2 * u2 + CB)); U[2] = C0 * u1 + (C1 * u2 + (C2 * u3 + CB)); U[3] = C0 * u2 + (C1 * u3 + (C2 * nu + CB));
; #pragma unroll
;                     for (int m = 0; m < 4; ++m) {
;                         const f32x2 t = G[m] * (-1.4426950408889634f);
;                         f32x2 e; e.x = __builtin_amdgcn_exp2f(t.x); e.y = __builtin_amdgcn_exp2f(t.y);
;                         const f32x2 d = e + 1.0f;
;                         f32x2 r; r.x = __builtin_amdgcn_rcpf(d.x); r.y = __builtin_amdgcn_rcpf(d.y);
;                         const f32x2 q = (G[m] * U[m]) * r;
;                         o[m][2 * h] = q.x; o[m][2 * h + 1] = q.y;
;                     }
;     ...
;                 }
; #pragma unroll
;                 for (int m = 0; m < 4; ++m) { ow[m][2 * n] = cvt_pk_bf16(o[m][0], o[m][1]); ow[m][2 * n + 1] = cvt_pk_bf16(o[m][2], o[m][3]); }
;             }
; #pragma unroll
;             for (int m = 0; m < 4; ++m) { u32x4 w; w.x = ow[m][0]; w.y = ow[m][1]; w.z = ow[m][2]; w.w = ow[m][3];
;                 *(u32x4*)(ACT + (size_t)(rowb + ai * HALF + m) * DFF_ + ch0) = w; }
	v_fma_f32 v18, v54, v98, v58
	v_fma_f32 v19, v55, v99, v59
	v_rcp_f32_e32 v16, v16
	v_rcp_f32_e32 v17, v17
	v_fma_f32 v18, v70, v40, v18
	v_fma_f32 v19, v71, v41, v19
	v_mov_b32_dpp v102, v66 row_shr:1 row_mask:0xf bank_mask:0xf
	v_fma_f32 v18, v74, v36, v18
	v_fma_f32 v19, v75, v37, v19
	v_mov_b32_dpp v103, v67 row_shr:1 row_mask:0xf bank_mask:0xf
	v_mul_f32 v12, v12, v18
	v_mul_f32 v13, v13, v19
	v_add_f32 v18, v22, 1.0
	v_add_f32 v19, v23, 1.0
	v_mul_f32 v12, v12, v16
	v_mul_f32 v13, v13, v17
	v_fma_f32 v16, v70, v54, v58
	v_fma_f32 v17, v71, v55, v59
	v_rcp_f32_e32 v18, v18
	v_rcp_f32_e32 v19, v19
	v_fma_f32 v16, v74, v40, v16
	v_fma_f32 v17, v75, v41, v17
	v_fma_f32 v22, v74, v54, v58
	v_fma_f32 v23, v75, v55, v59
	v_fma_f32 v16, v2, v36, v16
	v_fma_f32 v17, v3, v37, v17
	v_fma_f32 v22, v2, v40, v22
	v_fma_f32 v23, v3, v41, v23
	v_mul_f32 v16, v20, v16
	v_mul_f32 v17, v21, v17
	v_fma_f32 v22, v50, v36, v22
	v_fma_f32 v23, v51, v37, v23
	v_mul_f32 v16, v16, v18
	v_mul_f32 v17, v17, v19
	v_fma_f32 v18, v86, v82, v90
	v_fma_f32 v19, v87, v83, v91
	v_fma_f32 v2, v2, v54, v58
	v_fma_f32 v3, v3, v55, v59
	v_fma_f32 v18, v6, v78, v18
	v_fma_f32 v19, v7, v79, v19
	v_fma_f32 v6, v6, v82, v90
	v_fma_f32 v7, v7, v83, v91
	v_fma_f32 v18, v46, v62, v18
	v_fma_f32 v19, v47, v63, v19
	v_fma_f32 v6, v46, v78, v6
	v_fma_f32 v7, v47, v79, v7
	v_mul_f32 v20, v18, s0
	v_mul_f32 v21, v19, s0
	v_fma_f32 v6, v62, v102, v6
	v_fma_f32 v7, v63, v103, v7
	v_exp_f32_e32 v20, v20
	v_exp_f32_e32 v21, v21
	v_mul_f32 v24, v6, s0
	v_mul_f32 v25, v7, s0
	v_mul_f32 v18, v18, v22
	v_mul_f32 v19, v19, v23
	v_exp_f32_e32 v24, v24
	v_add_f32 v20, v20, 1.0
	v_add_f32 v21, v21, 1.0
	v_exp_f32_e32 v25, v25
	v_rcp_f32_e32 v20, v20
	v_rcp_f32_e32 v21, v21
	v_mov_b32_dpp v94, v70 row_shr:1 row_mask:0xf bank_mask:0xf
	v_mov_b32_dpp v95, v71 row_shr:1 row_mask:0xf bank_mask:0xf
	v_fma_f32 v2, v50, v40, v2
	v_fma_f32 v3, v51, v41, v3
	v_mul_f32 v18, v18, v20
	v_mul_f32 v19, v19, v21
	v_add_f32 v20, v24, 1.0
	v_add_f32 v21, v25, 1.0
	v_fma_f32 v2, v36, v94, v2
	v_fma_f32 v3, v37, v95, v3
	v_rcp_f32_e32 v20, v20
	v_rcp_f32_e32 v21, v21
	v_mul_f32 v2, v6, v2
	v_mul_f32 v3, v7, v3
	v_fma_f32 v6, v8, v84, v92
	v_fma_f32 v7, v9, v85, v93
	v_fma_f32 v22, v68, v84, v92
	v_fma_f32 v23, v69, v85, v93
	v_mul_f32 v2, v2, v20
	v_mul_f32 v3, v3, v21
	v_fma_f32 v20, v88, v84, v92
	v_fma_f32 v21, v89, v85, v93
	v_fma_f32 v24, v4, v56, v60
	v_fma_f32 v25, v5, v57, v61
	v_mov_b32_dpp v104, v68 row_shr:1 row_mask:0xf bank_mask:0xf
	v_mov_b32_dpp v105, v69 row_shr:1 row_mask:0xf bank_mask:0xf
	v_mov_b32_dpp v96, v72 row_shr:1 row_mask:0xf bank_mask:0xf
	v_mov_b32_dpp v97, v73 row_shr:1 row_mask:0xf bank_mask:0xf
	v_fma_f32 v6, v48, v80, v6
	v_fma_f32 v7, v49, v81, v7
	v_fma_f32 v20, v8, v80, v20
	v_fma_f32 v21, v9, v81, v21
	v_fma_f32 v22, v88, v80, v22
	v_fma_f32 v23, v89, v81, v23
	v_fma_f32 v24, v52, v42, v24
	v_fma_f32 v25, v53, v43, v25
	v_mov_b32_dpp v28, v48 row_shl:1 row_mask:0xf bank_mask:0xf
	v_mov_b32_dpp v29, v49 row_shl:1 row_mask:0xf bank_mask:0xf
	v_fma_f32 v6, v64, v104, v6
	v_fma_f32 v7, v65, v105, v7
	v_fma_f32 v20, v48, v64, v20
	v_fma_f32 v21, v49, v65, v21
	v_fma_f32 v8, v8, v64, v22
	v_fma_f32 v9, v9, v65, v23
	v_fma_f32 v24, v38, v96, v24
	v_fma_f32 v25, v39, v97, v25
	v_fma_f32 v22, v84, v28, v92
	v_fma_f32 v23, v85, v29, v93
	v_fma_f32 v26, v76, v56, v60
	v_fma_f32 v27, v77, v57, v61
	v_mul_f32 v32, v6, s0
	v_mul_f32 v33, v7, s0
	v_mul_f32 v36, v20, s0
	v_mul_f32 v37, v21, s0
	v_mul_f32 v6, v6, v24
	v_mul_f32 v7, v7, v25
	v_mul_f32 v24, v8, s0
	v_mul_f32 v25, v9, s0
	v_fma_f32 v22, v68, v80, v22
	v_fma_f32 v23, v69, v81, v23
	v_fma_f32 v26, v4, v42, v26
	v_fma_f32 v27, v5, v43, v27
	v_exp_f32_e32 v36, v36
	v_exp_f32_e32 v37, v37
	v_exp_f32_e32 v24, v24
	v_exp_f32_e32 v25, v25
	v_fma_f32 v22, v88, v64, v22
	v_fma_f32 v23, v89, v65, v23
	v_fma_f32 v26, v52, v38, v26
	v_fma_f32 v27, v53, v39, v27
	v_exp_f32_e32 v32, v32
	v_exp_f32_e32 v33, v33
	v_mul_f32 v20, v20, v26
	v_mul_f32 v21, v21, v27
	v_mul_f32 v26, v22, s0
	v_mul_f32 v27, v23, s0
	v_add_f32 v36, v36, 1.0
	v_add_f32 v37, v37, 1.0
	v_exp_f32_e32 v26, v26
	v_exp_f32_e32 v27, v27
	v_add_f32 v24, v24, 1.0
	v_add_f32 v25, v25, 1.0
	v_fma_f32 v28, v72, v56, v60
	v_fma_f32 v29, v73, v57, v61
	v_add_f32 v32, v32, 1.0
	v_add_f32 v33, v33, 1.0
	v_rcp_f32_e32 v36, v36
	v_rcp_f32_e32 v37, v37
	v_rcp_f32_e32 v24, v24
	v_rcp_f32_e32 v25, v25
	v_fma_f32 v28, v76, v42, v28
	v_fma_f32 v29, v77, v43, v29
	v_rcp_f32_e32 v32, v32
	v_rcp_f32_e32 v33, v33
	v_mov_b32_dpp v100, v52 row_shl:1 row_mask:0xf bank_mask:0xf
	v_mov_b32_dpp v101, v53 row_shl:1 row_mask:0xf bank_mask:0xf
	v_fma_f32 v4, v4, v38, v28
	v_fma_f32 v5, v5, v39, v29
	v_add_f32 v26, v26, 1.0
	v_add_f32 v27, v27, 1.0
	v_readlane_b32 s0, v252, 18
	v_fma_f32 v28, v56, v100, v60
	v_fma_f32 v29, v57, v101, v61
	v_rcp_f32_e32 v26, v26
	v_rcp_f32_e32 v27, v27
	v_mul_f32 v4, v8, v4
	v_mul_f32 v5, v9, v5
	v_readlane_b32 s1, v252, 19
	v_add_u32_e32 v44, 0x80, v220
	v_fma_f32 v28, v72, v42, v28
	v_fma_f32 v29, v73, v43, v29
	v_mul_f32 v20, v20, v36
	v_mul_f32 v21, v21, v37
	v_mul_f32 v4, v4, v24
	v_mul_f32 v5, v5, v25
	v_cvt_pk_bf16_f32 v36, v2, v3
	v_mov_b64_e32 v[2:3], s[0:1]
	s_movk_i32 s4, 0x2c00
	v_fma_f32 v28, v76, v38, v28
	v_fma_f32 v29, v77, v39, v29
	v_mul_f32 v6, v6, v32
	v_mul_f32 v7, v7, v33
	v_add_u32_e32 v45, 0x81, v220
	v_cvt_pk_bf16_f32 v37, v6, v7
	v_cvt_pk_bf16_f32 v32, v18, v19
	v_cvt_pk_bf16_f32 v33, v20, v21
	v_cvt_pk_bf16_f32 v16, v16, v17
	v_cvt_pk_bf16_f32 v17, v4, v5
	v_mad_i64_i32 v[4:5], s[0:1], v44, s4, v[2:3]
	v_mul_f32 v8, v22, v28
	v_mul_f32 v9, v23, v29
	v_lshl_add_u64 v[4:5], v[4:5], 0, v[142:143]
	v_mul_f32 v8, v8, v26
	v_mul_f32 v9, v9, v27
	v_cvt_pk_bf16_f32 v12, v12, v13
	v_add_u32_e32 v106, 0x82, v220
	v_cvt_pk_bf16_f32 v13, v8, v9
	global_store_dwordx4 v[4:5], v[34:37], off
	v_mad_i64_i32 v[4:5], s[0:1], v45, s4, v[2:3]
	v_add_u32_e32 v107, 0x83, v220
	v_lshl_add_u64 v[4:5], v[4:5], 0, v[142:143]
	global_store_dwordx4 v[4:5], v[30:33], off
	v_mad_i64_i32 v[4:5], s[0:1], v106, s4, v[2:3]
	v_mad_i64_i32 v[2:3], s[0:1], v107, s4, v[2:3]
	v_lshl_add_u64 v[4:5], v[4:5], 0, v[142:143]
	v_lshl_add_u64 v[2:3], v[2:3], 0, v[142:143]
	global_store_dwordx4 v[4:5], v[14:17], off
	global_store_dwordx4 v[2:3], v[10:13], off
	v_readlane_b32 s0, v254, 42
	v_readlane_b32 s1, v254, 43
	s_andn2_b64 vcc, exec, s[0:1]
	s_mov_b64 s[0:1], -1
	s_cbranch_vccnz .LBB0_76
	s_and_b64 vcc, exec, s[8:9]
	s_cbranch_vccnz .LBB0_75
	s_barrier
	s_branch .LBB0_75
